# loader-segment scalar set-up before the first DMA issued at the tail of the preceding MMA segment
# speedup vs baseline: 1.0015x; 1.0015x over previous
;     __device__ __forceinline__ void prep(int pm, int par, LAS unsigned char* lds) const { if (fold) prep_rowstats(stat, pm, par, lds); }
;     __device__ __forceinline__ void prep(int pm, int par, LAS unsigned char* lds) const { if (!ident) prep_rowstats(stat, pm, par, lds); }
;     __device__ __forceinline__ void prep(int pm, int par, LAS unsigned char* lds) const { prep_rowstats(stat, pm, par, lds); }
; #define G_STAGE(bufoff, gbase) do { _Pragma("unroll") for (int _i = 0; _i < 2; ++_i) \
;         __builtin_amdgcn_global_load_lds((const unsigned*)((const char*)(gbase) + voff[_i]), (LAS unsigned*)(lds + (bufoff) + ldsw + _i * 8192), 16, 0, 0); } while (0)
; #define G_LDA(dst, b, h) do { _Pragma("unroll") for (int m = 0; m < 4; ++m) _Pragma("unroll") for (int k = 0; k < 2; ++k) dst[m][k] = *(const LAS bf16x8*)(lds + G_SA(b, h) + aoff + m * 2048 + k * 1024); } while (0)
; #define G_LDB(dst, b, h) do { _Pragma("unroll") for (int n = 0; n < 2; ++n) _Pragma("unroll") for (int k = 0; k < 2; ++k) dst[n][k] = *(const LAS bf16x8*)(lds + G_SB(b, h) + boff + n * 2048 + k * 1024); } while (0)
; #define G_WAIT_V(n) asm volatile("s_waitcnt vmcnt(" #n ")" ::: "memory")
; #define G_WAIT_L(n) asm volatile("s_waitcnt lgkmcnt(" #n ")" ::: "memory")
; #define G_BAR __builtin_amdgcn_s_barrier()
; #define G_SCHED __builtin_amdgcn_sched_barrier(0)
; template <class Epi>
; __device__ __forceinline__ void gemm_phase(LAS unsigned char* lds, const bf16_t* Ag, const bf16_t* Btg, const int K, const int nM, const int nN, const Epi& E) {
;     ...
;             const char* a2 = last ? nA : cA + (size_t)(t + 2) * kstep; const char* b2 = last ? nB : cB + (size_t)(t + 2) * kstep;
;             const char* a3 = a2 + kstep; const char* b3 = b2 + kstep;
;             if (last && has_next && pmn != pm) E.prep(pmn, par ^ 1, lds);
;             G_LDB(B0, 0, 0); G_SCHED; G_LDA(At, 0, 0); G_STAGE(G_SA(1, 1), a1 + hstep);
;             G_WAIT_L(8); G_BAR; G_WAIT_L(0); G_MMA(0, 0, At, B0); G_BAR; G_SCHED;
;             G_LDB(B1, 0, 1); G_STAGE(G_SB(0, 0), b2);
;             G_BAR; G_WAIT_L(0); G_MMA(0, 1, At, B1); G_BAR;
;             G_LDA(At, 0, 1); G_STAGE(G_SA(0, 0), a2);
;             G_BAR; G_WAIT_L(0); G_MMA(1, 0, At, B0); G_BAR; G_SCHED;
;             G_STAGE(G_SB(0, 1), b2 + hstep);
;             G_WAIT_V(6); G_BAR; G_MMA(1, 1, At, B1); G_BAR;
.LBB0_78:
	s_add_u32 s12, s50, 0xfffc0080
	s_addc_u32 s26, s51, -1
	s_and_b64 s[52:53], s[52:53], exec
	s_cselect_b32 s55, s26, s43
	s_cselect_b32 s54, s12, s42
	s_cselect_b32 s53, s72, s15
	s_cselect_b32 s52, s71, s69
	s_add_i32 m0, s58, 0xc000
.LmainW_78:
	ds_read_b128 v[124:127], v217
	ds_read_b128 v[128:131], v217 offset:1024
	ds_read_b128 v[132:135], v217 offset:2048
	ds_read_b128 v[136:139], v217 offset:3072
	ds_read_b128 v[140:143], v186
	ds_read_b128 v[148:151], v186 offset:1024
	ds_read_b128 v[152:155], v186 offset:2048
	ds_read_b128 v[156:159], v186 offset:3072
	ds_read_b128 v[188:191], v186 offset:4096
	ds_read_b128 v[192:195], v186 offset:5120
	ds_read_b128 v[222:225], v186 offset:6144
	global_load_lds_dwordx4 v170, s[50:51]
	s_add_i32 m0, s58, 0xe000
	ds_read_b128 v[226:229], v186 offset:7168
	global_load_lds_dwordx4 v168, s[50:51]
	s_waitcnt lgkmcnt(8)
	s_barrier
	s_waitcnt lgkmcnt(0)
	v_mfma_f32_16x16x32_bf16 v[164:167], v[124:127], v[140:143], v[164:167]
	v_mfma_f32_16x16x32_bf16 v[160:163], v[132:135], v[140:143], v[160:163]
	v_mfma_f32_16x16x32_bf16 v[116:119], v[124:127], v[152:155], v[116:119]
	v_mfma_f32_16x16x32_bf16 v[112:115], v[132:135], v[152:155], v[112:115]
	v_mfma_f32_16x16x32_bf16 v[100:103], v[124:127], v[188:191], v[100:103]
	v_mfma_f32_16x16x32_bf16 v[96:99], v[132:135], v[188:191], v[96:99]
	v_mfma_f32_16x16x32_bf16 v[84:87], v[124:127], v[222:225], v[84:87]
	v_mfma_f32_16x16x32_bf16 v[80:83], v[132:135], v[222:225], v[80:83]
	v_mfma_f32_16x16x32_bf16 v[164:167], v[128:131], v[148:151], v[164:167]
	v_mfma_f32_16x16x32_bf16 v[160:163], v[136:139], v[148:151], v[160:163]
	v_mfma_f32_16x16x32_bf16 v[116:119], v[128:131], v[156:159], v[116:119]
	v_mfma_f32_16x16x32_bf16 v[112:115], v[136:139], v[156:159], v[112:115]
	v_mfma_f32_16x16x32_bf16 v[100:103], v[128:131], v[192:195], v[100:103]
	v_mfma_f32_16x16x32_bf16 v[96:99], v[136:139], v[192:195], v[96:99]
	v_mfma_f32_16x16x32_bf16 v[84:87], v[128:131], v[226:229], v[84:87]
	v_mfma_f32_16x16x32_bf16 v[80:83], v[136:139], v[226:229], v[80:83]
	s_add_i32 m0, s57, 0x10000
	s_barrier
	ds_read_b128 v[230:233], v217 offset:16384
	ds_read_b128 v[234:237], v217 offset:17408
	ds_read_b128 v[238:241], v217 offset:18432
	global_load_lds_dwordx4 v0, s[52:53]
	s_add_i32 m0, s57, 0x12000
	ds_read_b128 v[242:245], v217 offset:19456
	global_load_lds_dwordx4 v2, s[52:53]
	s_barrier
	s_waitcnt lgkmcnt(0)
	v_mfma_f32_16x16x32_bf16 v[144:147], v[230:233], v[140:143], v[144:147]
	v_mfma_f32_16x16x32_bf16 v[120:123], v[238:241], v[140:143], v[120:123]
	v_mfma_f32_16x16x32_bf16 v[108:111], v[230:233], v[152:155], v[108:111]
	v_mfma_f32_16x16x32_bf16 v[104:107], v[238:241], v[152:155], v[104:107]
	v_mfma_f32_16x16x32_bf16 v[92:95], v[230:233], v[188:191], v[92:95]
	v_mfma_f32_16x16x32_bf16 v[88:91], v[238:241], v[188:191], v[88:91]
	v_mfma_f32_16x16x32_bf16 v[76:79], v[230:233], v[222:225], v[76:79]
	v_mfma_f32_16x16x32_bf16 v[72:75], v[238:241], v[222:225], v[72:75]
	v_mfma_f32_16x16x32_bf16 v[144:147], v[234:237], v[148:151], v[144:147]
	v_mfma_f32_16x16x32_bf16 v[120:123], v[242:245], v[148:151], v[120:123]
	v_mfma_f32_16x16x32_bf16 v[108:111], v[234:237], v[156:159], v[108:111]
	v_mfma_f32_16x16x32_bf16 v[104:107], v[242:245], v[156:159], v[104:107]
	v_mfma_f32_16x16x32_bf16 v[92:95], v[234:237], v[192:195], v[92:95]
	v_mfma_f32_16x16x32_bf16 v[88:91], v[242:245], v[192:195], v[88:91]
	v_mfma_f32_16x16x32_bf16 v[76:79], v[234:237], v[226:229], v[76:79]
	v_mfma_f32_16x16x32_bf16 v[72:75], v[242:245], v[226:229], v[72:75]
	s_mov_b32 m0, s58
	s_barrier
	ds_read_b128 v[140:143], v186 offset:16384
	ds_read_b128 v[148:151], v186 offset:17408
	ds_read_b128 v[152:155], v186 offset:18432
	ds_read_b128 v[156:159], v186 offset:19456
	ds_read_b128 v[188:191], v186 offset:20480
	ds_read_b128 v[192:195], v186 offset:21504
	ds_read_b128 v[222:225], v186 offset:22528
	global_load_lds_dwordx4 v0, s[54:55]
	s_mov_b32 m0, s59
	ds_read_b128 v[226:229], v186 offset:23552
	global_load_lds_dwordx4 v2, s[54:55]
	s_barrier
	s_waitcnt lgkmcnt(0)
	v_mfma_f32_16x16x32_bf16 v[60:63], v[124:127], v[140:143], v[60:63]
	v_mfma_f32_16x16x32_bf16 v[56:59], v[132:135], v[140:143], v[56:59]
	v_mfma_f32_16x16x32_bf16 v[44:47], v[124:127], v[152:155], v[44:47]
	v_mfma_f32_16x16x32_bf16 v[40:43], v[132:135], v[152:155], v[40:43]
	v_mfma_f32_16x16x32_bf16 v[28:31], v[124:127], v[188:191], v[28:31]
	v_mfma_f32_16x16x32_bf16 v[24:27], v[132:135], v[188:191], v[24:27]
	v_mfma_f32_16x16x32_bf16 v[12:15], v[124:127], v[222:225], v[12:15]
	v_mfma_f32_16x16x32_bf16 v[8:11], v[132:135], v[222:225], v[8:11]
	v_mfma_f32_16x16x32_bf16 v[60:63], v[128:131], v[148:151], v[60:63]
	v_mfma_f32_16x16x32_bf16 v[56:59], v[136:139], v[148:151], v[56:59]
	v_mfma_f32_16x16x32_bf16 v[44:47], v[128:131], v[156:159], v[44:47]
	v_mfma_f32_16x16x32_bf16 v[40:43], v[136:139], v[156:159], v[40:43]
	v_mfma_f32_16x16x32_bf16 v[28:31], v[128:131], v[192:195], v[28:31]
	v_mfma_f32_16x16x32_bf16 v[24:27], v[136:139], v[192:195], v[24:27]
	v_mfma_f32_16x16x32_bf16 v[12:15], v[128:131], v[226:229], v[12:15]
	v_mfma_f32_16x16x32_bf16 v[8:11], v[136:139], v[226:229], v[8:11]
	s_add_i32 m0, s57, 0x14000
	s_add_u32 s74, s52, 0x40000
	s_addc_u32 s75, s53, 0
	s_barrier
	global_load_lds_dwordx4 v0, s[74:75]
	s_add_i32 m0, s57, 0x16000
	s_add_u32 s54, s54, 0x40000
	s_addc_u32 s55, s55, 0
	global_load_lds_dwordx4 v2, s[74:75]
	s_waitcnt vmcnt(6)
	s_barrier
; #define G_STAGE(bufoff, gbase) do { _Pragma("unroll") for (int _i = 0; _i < 2; ++_i) \
;         __builtin_amdgcn_global_load_lds((const unsigned*)((const char*)(gbase) + voff[_i]), (LAS unsigned*)(lds + (bufoff) + ldsw + _i * 8192), 16, 0, 0); } while (0)
; #define G_LDA(dst, b, h) do { _Pragma("unroll") for (int m = 0; m < 4; ++m) _Pragma("unroll") for (int k = 0; k < 2; ++k) dst[m][k] = *(const LAS bf16x8*)(lds + G_SA(b, h) + aoff + m * 2048 + k * 1024); } while (0)
; #define G_LDB(dst, b, h) do { _Pragma("unroll") for (int n = 0; n < 2; ++n) _Pragma("unroll") for (int k = 0; k < 2; ++k) dst[n][k] = *(const LAS bf16x8*)(lds + G_SB(b, h) + boff + n * 2048 + k * 1024); } while (0)
; #define G_MMA(ai, bj, At, Bt) do { __builtin_amdgcn_s_setprio(1); _Pragma("unroll") for (int m = 0; m < 4; ++m) _Pragma("unroll") for (int n = 0; n < 2; ++n) _Pragma("unroll") for (int k = 0; k < 2; ++k) \
;         acc[ai][bj][m][n] = MFMA16(Bt[n][k], At[m][k], acc[ai][bj][m][n]); __builtin_amdgcn_s_setprio(0); } while (0)
; #define G_WAIT_V(n) asm volatile("s_waitcnt vmcnt(" #n ")" ::: "memory")
; #define G_WAIT_L(n) asm volatile("s_waitcnt lgkmcnt(" #n ")" ::: "memory")
; #define G_BAR __builtin_amdgcn_s_barrier()
; #define G_SCHED __builtin_amdgcn_sched_barrier(0)
; template <class Epi>
; __device__ __forceinline__ void gemm_phase(LAS unsigned char* lds, const bf16_t* Ag, const bf16_t* Btg, const int K, const int nM, const int nN, const Epi& E) {
;     ...
;         for (int t = 0; t < nt; t += 2) {
;             const bool last = (t == nt - 2);
;             const char* a1 = cA + (size_t)(t + 1) * kstep;
;             const char* a2 = last ? nA : cA + (size_t)(t + 2) * kstep; const char* b2 = last ? nB : cB + (size_t)(t + 2) * kstep;
;             const char* a3 = a2 + kstep; const char* b3 = b2 + kstep;
;     ...
;             G_LDB(B0, 1, 0); G_SCHED; G_LDA(At, 1, 0); G_STAGE(G_SA(0, 1), a2 + hstep);
;             G_WAIT_L(8); G_BAR; G_WAIT_L(0); G_MMA(0, 0, At, B0); G_BAR; G_SCHED;
;             G_LDB(B1, 1, 1); G_STAGE(G_SB(1, 0), b3);
;             G_BAR; G_WAIT_L(0); G_MMA(0, 1, At, B1); G_BAR;
;             G_LDA(At, 1, 1); G_STAGE(G_SA(1, 0), a3);
;             G_BAR; G_WAIT_L(0); G_MMA(1, 0, At, B0); G_BAR; G_SCHED;
;             G_STAGE(G_SB(1, 1), b3 + hstep);
;             G_WAIT_V(6); G_BAR; G_MMA(1, 1, At, B1); G_BAR;
	v_mfma_f32_16x16x32_bf16 v[68:71], v[230:233], v[140:143], v[68:71]
	v_mfma_f32_16x16x32_bf16 v[64:67], v[238:241], v[140:143], v[64:67]
	v_mfma_f32_16x16x32_bf16 v[52:55], v[230:233], v[152:155], v[52:55]
	v_mfma_f32_16x16x32_bf16 v[48:51], v[238:241], v[152:155], v[48:51]
	v_mfma_f32_16x16x32_bf16 v[36:39], v[230:233], v[188:191], v[36:39]
	v_mfma_f32_16x16x32_bf16 v[32:35], v[238:241], v[188:191], v[32:35]
	v_mfma_f32_16x16x32_bf16 v[20:23], v[230:233], v[222:225], v[20:23]
	v_mfma_f32_16x16x32_bf16 v[16:19], v[238:241], v[222:225], v[16:19]
	v_mfma_f32_16x16x32_bf16 v[68:71], v[234:237], v[148:151], v[68:71]
	v_mfma_f32_16x16x32_bf16 v[64:67], v[242:245], v[148:151], v[64:67]
	v_mfma_f32_16x16x32_bf16 v[52:55], v[234:237], v[156:159], v[52:55]
	v_mfma_f32_16x16x32_bf16 v[48:51], v[242:245], v[156:159], v[48:51]
	v_mfma_f32_16x16x32_bf16 v[36:39], v[234:237], v[192:195], v[36:39]
	v_mfma_f32_16x16x32_bf16 v[32:35], v[242:245], v[192:195], v[32:35]
	v_mfma_f32_16x16x32_bf16 v[20:23], v[234:237], v[226:229], v[20:23]
	v_mfma_f32_16x16x32_bf16 v[16:19], v[242:245], v[226:229], v[16:19]
	s_mov_b32 m0, s60
	s_barrier
	ds_read_b128 v[124:127], v217 offset:32768
	ds_read_b128 v[128:131], v217 offset:33792
	ds_read_b128 v[132:135], v217 offset:34816
	ds_read_b128 v[136:139], v217 offset:35840
	ds_read_b128 v[140:143], v186 offset:32768
	ds_read_b128 v[148:151], v186 offset:33792
	ds_read_b128 v[152:155], v186 offset:34816
	ds_read_b128 v[156:159], v186 offset:35840
	ds_read_b128 v[188:191], v186 offset:36864
	ds_read_b128 v[192:195], v186 offset:37888
	ds_read_b128 v[222:225], v186 offset:38912
	global_load_lds_dwordx4 v0, s[54:55]
	s_mov_b32 m0, s61
	ds_read_b128 v[226:229], v186 offset:39936
	global_load_lds_dwordx4 v2, s[54:55]
	s_waitcnt lgkmcnt(8)
	s_barrier
	s_waitcnt lgkmcnt(0)
	v_mfma_f32_16x16x32_bf16 v[164:167], v[124:127], v[140:143], v[164:167]
	v_mfma_f32_16x16x32_bf16 v[160:163], v[132:135], v[140:143], v[160:163]
	v_mfma_f32_16x16x32_bf16 v[116:119], v[124:127], v[152:155], v[116:119]
	v_mfma_f32_16x16x32_bf16 v[112:115], v[132:135], v[152:155], v[112:115]
	v_mfma_f32_16x16x32_bf16 v[100:103], v[124:127], v[188:191], v[100:103]
	v_mfma_f32_16x16x32_bf16 v[96:99], v[132:135], v[188:191], v[96:99]
	v_mfma_f32_16x16x32_bf16 v[84:87], v[124:127], v[222:225], v[84:87]
	v_mfma_f32_16x16x32_bf16 v[80:83], v[132:135], v[222:225], v[80:83]
	v_mfma_f32_16x16x32_bf16 v[164:167], v[128:131], v[148:151], v[164:167]
	v_mfma_f32_16x16x32_bf16 v[160:163], v[136:139], v[148:151], v[160:163]
	v_mfma_f32_16x16x32_bf16 v[116:119], v[128:131], v[156:159], v[116:119]
	v_mfma_f32_16x16x32_bf16 v[112:115], v[136:139], v[156:159], v[112:115]
	v_mfma_f32_16x16x32_bf16 v[100:103], v[128:131], v[192:195], v[100:103]
	v_mfma_f32_16x16x32_bf16 v[96:99], v[136:139], v[192:195], v[96:99]
	v_mfma_f32_16x16x32_bf16 v[84:87], v[128:131], v[226:229], v[84:87]
	v_mfma_f32_16x16x32_bf16 v[80:83], v[136:139], v[226:229], v[80:83]
	s_add_i32 m0, s57, 0x18000
	s_add_u32 s98, s52, 0x80
	s_addc_u32 s99, s53, 0
	s_barrier
	ds_read_b128 v[230:233], v217 offset:49152
	ds_read_b128 v[234:237], v217 offset:50176
	ds_read_b128 v[238:241], v217 offset:51200
	global_load_lds_dwordx4 v0, s[98:99]
	s_add_i32 m0, s57, 0x1a000
	ds_read_b128 v[242:245], v217 offset:52224
	global_load_lds_dwordx4 v2, s[98:99]
	s_barrier
	s_waitcnt lgkmcnt(0)
	v_mfma_f32_16x16x32_bf16 v[144:147], v[230:233], v[140:143], v[144:147]
	v_mfma_f32_16x16x32_bf16 v[120:123], v[238:241], v[140:143], v[120:123]
	v_mfma_f32_16x16x32_bf16 v[108:111], v[230:233], v[152:155], v[108:111]
	v_mfma_f32_16x16x32_bf16 v[104:107], v[238:241], v[152:155], v[104:107]
	v_mfma_f32_16x16x32_bf16 v[92:95], v[230:233], v[188:191], v[92:95]
	v_mfma_f32_16x16x32_bf16 v[88:91], v[238:241], v[188:191], v[88:91]
	v_mfma_f32_16x16x32_bf16 v[76:79], v[230:233], v[222:225], v[76:79]
	v_mfma_f32_16x16x32_bf16 v[72:75], v[238:241], v[222:225], v[72:75]
	v_mfma_f32_16x16x32_bf16 v[144:147], v[234:237], v[148:151], v[144:147]
	v_mfma_f32_16x16x32_bf16 v[120:123], v[242:245], v[148:151], v[120:123]
	v_mfma_f32_16x16x32_bf16 v[108:111], v[234:237], v[156:159], v[108:111]
	v_mfma_f32_16x16x32_bf16 v[104:107], v[242:245], v[156:159], v[104:107]
	v_mfma_f32_16x16x32_bf16 v[92:95], v[234:237], v[192:195], v[92:95]
	v_mfma_f32_16x16x32_bf16 v[88:91], v[242:245], v[192:195], v[88:91]
	v_mfma_f32_16x16x32_bf16 v[76:79], v[234:237], v[226:229], v[76:79]
	v_mfma_f32_16x16x32_bf16 v[72:75], v[242:245], v[226:229], v[72:75]
	s_mov_b32 m0, s62
	s_add_u32 s98, s54, 0xfffc0080
	s_addc_u32 s99, s55, -1
	s_barrier
	ds_read_b128 v[140:143], v186 offset:49152
	ds_read_b128 v[148:151], v186 offset:50176
	ds_read_b128 v[152:155], v186 offset:51200
	ds_read_b128 v[156:159], v186 offset:52224
	ds_read_b128 v[188:191], v186 offset:53248
	ds_read_b128 v[192:195], v186 offset:54272
	ds_read_b128 v[222:225], v186 offset:55296
	global_load_lds_dwordx4 v0, s[98:99]
	s_mov_b32 m0, s63
	ds_read_b128 v[226:229], v186 offset:56320
	global_load_lds_dwordx4 v2, s[98:99]
	s_barrier
	s_waitcnt lgkmcnt(0)
	v_mfma_f32_16x16x32_bf16 v[60:63], v[124:127], v[140:143], v[60:63]
	v_mfma_f32_16x16x32_bf16 v[56:59], v[132:135], v[140:143], v[56:59]
	v_mfma_f32_16x16x32_bf16 v[44:47], v[124:127], v[152:155], v[44:47]
	v_mfma_f32_16x16x32_bf16 v[40:43], v[132:135], v[152:155], v[40:43]
	v_mfma_f32_16x16x32_bf16 v[28:31], v[124:127], v[188:191], v[28:31]
	v_mfma_f32_16x16x32_bf16 v[24:27], v[132:135], v[188:191], v[24:27]
	v_mfma_f32_16x16x32_bf16 v[12:15], v[124:127], v[222:225], v[12:15]
	v_mfma_f32_16x16x32_bf16 v[8:11], v[132:135], v[222:225], v[8:11]
	v_mfma_f32_16x16x32_bf16 v[60:63], v[128:131], v[148:151], v[60:63]
	v_mfma_f32_16x16x32_bf16 v[56:59], v[136:139], v[148:151], v[56:59]
	v_mfma_f32_16x16x32_bf16 v[44:47], v[128:131], v[156:159], v[44:47]
	v_mfma_f32_16x16x32_bf16 v[40:43], v[136:139], v[156:159], v[40:43]
	v_mfma_f32_16x16x32_bf16 v[28:31], v[128:131], v[192:195], v[28:31]
	v_mfma_f32_16x16x32_bf16 v[24:27], v[136:139], v[192:195], v[24:27]
	v_mfma_f32_16x16x32_bf16 v[12:15], v[128:131], v[226:229], v[12:15]
	v_mfma_f32_16x16x32_bf16 v[8:11], v[136:139], v[226:229], v[8:11]
	s_add_i32 m0, s57, 0x1c000
	s_add_u32 s52, s52, 0x40080
	s_addc_u32 s53, s53, 0
	s_barrier
	global_load_lds_dwordx4 v0, s[52:53]
	s_add_i32 m0, s57, 0x1e000
	s_add_i32 s73, s73, 2
	global_load_lds_dwordx4 v2, s[52:53]
	s_add_u32 s71, s71, 0x100
	s_addc_u32 s72, s72, 0
	s_add_u32 s50, s50, 0x100
	s_addc_u32 s51, s51, 0
	s_cmp_gt_u32 s73, 13
	s_cbranch_scc1 .LrotX_78
	s_add_u32 s12, s50, 0xfffc0080
	s_addc_u32 s26, s51, -1
	s_cmp_lg_u32 s73, 12
	s_cselect_b32 s55, s26, s43
	s_cselect_b32 s54, s12, s42
	s_cselect_b32 s53, s72, s15
	s_cselect_b32 s52, s71, s69
; #define G_STAGE(bufoff, gbase) do { _Pragma("unroll") for (int _i = 0; _i < 2; ++_i) \
;         __builtin_amdgcn_global_load_lds((const unsigned*)((const char*)(gbase) + voff[_i]), (LAS unsigned*)(lds + (bufoff) + ldsw + _i * 8192), 16, 0, 0); } while (0)
; #define G_MMA(ai, bj, At, Bt) do { __builtin_amdgcn_s_setprio(1); _Pragma("unroll") for (int m = 0; m < 4; ++m) _Pragma("unroll") for (int n = 0; n < 2; ++n) _Pragma("unroll") for (int k = 0; k < 2; ++k) \
;         acc[ai][bj][m][n] = MFMA16(Bt[n][k], At[m][k], acc[ai][bj][m][n]); __builtin_amdgcn_s_setprio(0); } while (0)
; #define G_WAIT_V(n) asm volatile("s_waitcnt vmcnt(" #n ")" ::: "memory")
; #define G_BAR __builtin_amdgcn_s_barrier()
; template <class Epi>
; __device__ __forceinline__ void gemm_phase(LAS unsigned char* lds, const bf16_t* Ag, const bf16_t* Btg, const int K, const int nM, const int nN, const Epi& E) {
;     ...
;             G_STAGE(G_SB(1, 1), b3 + hstep);
;             G_WAIT_V(6); G_BAR; G_MMA(1, 1, At, B1); G_BAR;
;         }
.LrotX_78:
	s_waitcnt vmcnt(6)
	s_barrier
	v_mfma_f32_16x16x32_bf16 v[68:71], v[230:233], v[140:143], v[68:71]
	v_mfma_f32_16x16x32_bf16 v[64:67], v[238:241], v[140:143], v[64:67]
	v_mfma_f32_16x16x32_bf16 v[52:55], v[230:233], v[152:155], v[52:55]
	v_mfma_f32_16x16x32_bf16 v[48:51], v[238:241], v[152:155], v[48:51]
	v_mfma_f32_16x16x32_bf16 v[36:39], v[230:233], v[188:191], v[36:39]
	v_mfma_f32_16x16x32_bf16 v[32:35], v[238:241], v[188:191], v[32:35]
	v_mfma_f32_16x16x32_bf16 v[20:23], v[230:233], v[222:225], v[20:23]
	v_mfma_f32_16x16x32_bf16 v[16:19], v[238:241], v[222:225], v[16:19]
	v_mfma_f32_16x16x32_bf16 v[68:71], v[234:237], v[148:151], v[68:71]
	v_mfma_f32_16x16x32_bf16 v[64:67], v[242:245], v[148:151], v[64:67]
	v_mfma_f32_16x16x32_bf16 v[52:55], v[234:237], v[156:159], v[52:55]
	v_mfma_f32_16x16x32_bf16 v[48:51], v[242:245], v[156:159], v[48:51]
	v_mfma_f32_16x16x32_bf16 v[36:39], v[234:237], v[192:195], v[36:39]
	v_mfma_f32_16x16x32_bf16 v[32:35], v[242:245], v[192:195], v[32:35]
	v_mfma_f32_16x16x32_bf16 v[20:23], v[234:237], v[226:229], v[20:23]
	v_mfma_f32_16x16x32_bf16 v[16:19], v[242:245], v[226:229], v[16:19]
	s_add_i32 m0, s58, 0xc000
	s_cmp_lt_u32 s73, 12
	s_barrier
	s_cbranch_scc1 .LmainW_78
	s_cmp_gt_u32 s73, 13
	s_cbranch_scc1 .LBB0_82

;     __device__ __forceinline__ void prep(int pm, int par, LAS unsigned char* lds) const { if (fold) prep_rowstats(stat, pm, par, lds); }
;     __device__ __forceinline__ void prep(int pm, int par, LAS unsigned char* lds) const { if (!ident) prep_rowstats(stat, pm, par, lds); }
;     __device__ __forceinline__ void prep(int pm, int par, LAS unsigned char* lds) const { prep_rowstats(stat, pm, par, lds); }
; #define G_STAGE(bufoff, gbase) do { _Pragma("unroll") for (int _i = 0; _i < 2; ++_i) \
;         __builtin_amdgcn_global_load_lds((const unsigned*)((const char*)(gbase) + voff[_i]), (LAS unsigned*)(lds + (bufoff) + ldsw + _i * 8192), 16, 0, 0); } while (0)
; #define G_LDA(dst, b, h) do { _Pragma("unroll") for (int m = 0; m < 4; ++m) _Pragma("unroll") for (int k = 0; k < 2; ++k) dst[m][k] = *(const LAS bf16x8*)(lds + G_SA(b, h) + aoff + m * 2048 + k * 1024); } while (0)
; #define G_LDB(dst, b, h) do { _Pragma("unroll") for (int n = 0; n < 2; ++n) _Pragma("unroll") for (int k = 0; k < 2; ++k) dst[n][k] = *(const LAS bf16x8*)(lds + G_SB(b, h) + boff + n * 2048 + k * 1024); } while (0)
; #define G_WAIT_V(n) asm volatile("s_waitcnt vmcnt(" #n ")" ::: "memory")
; #define G_WAIT_L(n) asm volatile("s_waitcnt lgkmcnt(" #n ")" ::: "memory")
; #define G_BAR __builtin_amdgcn_s_barrier()
; #define G_SCHED __builtin_amdgcn_sched_barrier(0)
; template <class Epi>
; __device__ __forceinline__ void gemm_phase(LAS unsigned char* lds, const bf16_t* Ag, const bf16_t* Btg, const int K, const int nM, const int nN, const Epi& E) {
;     ...
;             const char* a2 = last ? nA : cA + (size_t)(t + 2) * kstep; const char* b2 = last ? nB : cB + (size_t)(t + 2) * kstep;
;             const char* a3 = a2 + kstep; const char* b3 = b2 + kstep;
;             if (last && has_next && pmn != pm) E.prep(pmn, par ^ 1, lds);
;             G_LDB(B0, 0, 0); G_SCHED; G_LDA(At, 0, 0); G_STAGE(G_SA(1, 1), a1 + hstep);
;             G_WAIT_L(8); G_BAR; G_WAIT_L(0); G_MMA(0, 0, At, B0); G_BAR; G_SCHED;
;             G_LDB(B1, 0, 1); G_STAGE(G_SB(0, 0), b2);
;             G_BAR; G_WAIT_L(0); G_MMA(0, 1, At, B1); G_BAR;
;             G_LDA(At, 0, 1); G_STAGE(G_SA(0, 0), a2);
;             G_BAR; G_WAIT_L(0); G_MMA(1, 0, At, B0); G_BAR; G_SCHED;
;             G_STAGE(G_SB(0, 1), b2 + hstep);
;             G_WAIT_V(6); G_BAR; G_MMA(1, 1, At, B1); G_BAR;
.LBB0_153:
	s_add_u32 s66, s64, 0x100
	s_addc_u32 s67, s65, 0
	s_and_b64 s[68:69], s[68:69], exec
	s_cselect_b32 s71, s67, s55
	s_cselect_b32 s70, s66, s54
	s_cselect_b32 s69, s61, s14
	s_cselect_b32 s68, s57, s15
	s_add_i32 m0, s72, 0xc000
.LmainW_153:
	ds_read_b128 v[144:147], v217
	ds_read_b128 v[148:151], v217 offset:1024
	ds_read_b128 v[152:155], v217 offset:2048
	ds_read_b128 v[156:159], v217 offset:3072
	ds_read_b128 v[160:163], v230
	ds_read_b128 v[164:167], v230 offset:1024
	ds_read_b128 v[168:171], v230 offset:2048
	ds_read_b128 v[172:175], v230 offset:3072
	ds_read_b128 v[180:183], v230 offset:4096
	ds_read_b128 v[184:187], v230 offset:5120
	ds_read_b128 v[188:191], v230 offset:6144
	global_load_lds_dwordx4 v138, s[64:65]
	s_add_i32 m0, s72, 0xe000
	ds_read_b128 v[192:195], v230 offset:7168
	global_load_lds_dwordx4 v136, s[64:65]
	s_waitcnt lgkmcnt(8)
	s_barrier
	s_waitcnt lgkmcnt(0)
	v_mfma_f32_16x16x32_bf16 v[132:135], v[144:147], v[160:163], v[132:135]
	v_mfma_f32_16x16x32_bf16 v[128:131], v[152:155], v[160:163], v[128:131]
	v_mfma_f32_16x16x32_bf16 v[116:119], v[144:147], v[168:171], v[116:119]
	v_mfma_f32_16x16x32_bf16 v[112:115], v[152:155], v[168:171], v[112:115]
	v_mfma_f32_16x16x32_bf16 v[100:103], v[144:147], v[180:183], v[100:103]
	v_mfma_f32_16x16x32_bf16 v[96:99], v[152:155], v[180:183], v[96:99]
	v_mfma_f32_16x16x32_bf16 v[84:87], v[144:147], v[188:191], v[84:87]
	v_mfma_f32_16x16x32_bf16 v[80:83], v[152:155], v[188:191], v[80:83]
	v_mfma_f32_16x16x32_bf16 v[132:135], v[148:151], v[164:167], v[132:135]
	v_mfma_f32_16x16x32_bf16 v[128:131], v[156:159], v[164:167], v[128:131]
	v_mfma_f32_16x16x32_bf16 v[116:119], v[148:151], v[172:175], v[116:119]
	v_mfma_f32_16x16x32_bf16 v[112:115], v[156:159], v[172:175], v[112:115]
	v_mfma_f32_16x16x32_bf16 v[100:103], v[148:151], v[184:187], v[100:103]
	v_mfma_f32_16x16x32_bf16 v[96:99], v[156:159], v[184:187], v[96:99]
	v_mfma_f32_16x16x32_bf16 v[84:87], v[148:151], v[192:195], v[84:87]
	v_mfma_f32_16x16x32_bf16 v[80:83], v[156:159], v[192:195], v[80:83]
	s_add_i32 m0, s21, 0x10000
	s_barrier
	ds_read_b128 v[232:235], v217 offset:16384
	ds_read_b128 v[236:239], v217 offset:17408
	ds_read_b128 v[240:243], v217 offset:18432
	global_load_lds_dwordx4 v0, s[68:69]
	s_add_i32 m0, s21, 0x12000
	ds_read_b128 v[244:247], v217 offset:19456
	global_load_lds_dwordx4 v2, s[68:69]
	s_barrier
	s_waitcnt lgkmcnt(0)
	v_mfma_f32_16x16x32_bf16 v[124:127], v[232:235], v[160:163], v[124:127]
	v_mfma_f32_16x16x32_bf16 v[120:123], v[240:243], v[160:163], v[120:123]
	v_mfma_f32_16x16x32_bf16 v[108:111], v[232:235], v[168:171], v[108:111]
	v_mfma_f32_16x16x32_bf16 v[104:107], v[240:243], v[168:171], v[104:107]
	v_mfma_f32_16x16x32_bf16 v[92:95], v[232:235], v[180:183], v[92:95]
	v_mfma_f32_16x16x32_bf16 v[88:91], v[240:243], v[180:183], v[88:91]
	v_mfma_f32_16x16x32_bf16 v[76:79], v[232:235], v[188:191], v[76:79]
	v_mfma_f32_16x16x32_bf16 v[72:75], v[240:243], v[188:191], v[72:75]
	v_mfma_f32_16x16x32_bf16 v[124:127], v[236:239], v[164:167], v[124:127]
	v_mfma_f32_16x16x32_bf16 v[120:123], v[244:247], v[164:167], v[120:123]
	v_mfma_f32_16x16x32_bf16 v[108:111], v[236:239], v[172:175], v[108:111]
	v_mfma_f32_16x16x32_bf16 v[104:107], v[244:247], v[172:175], v[104:107]
	v_mfma_f32_16x16x32_bf16 v[92:95], v[236:239], v[184:187], v[92:95]
	v_mfma_f32_16x16x32_bf16 v[88:91], v[244:247], v[184:187], v[88:91]
	v_mfma_f32_16x16x32_bf16 v[76:79], v[236:239], v[192:195], v[76:79]
	v_mfma_f32_16x16x32_bf16 v[72:75], v[244:247], v[192:195], v[72:75]
	s_mov_b32 m0, s72
	s_barrier
	ds_read_b128 v[160:163], v230 offset:16384
	ds_read_b128 v[164:167], v230 offset:17408
	ds_read_b128 v[168:171], v230 offset:18432
	ds_read_b128 v[172:175], v230 offset:19456
	ds_read_b128 v[180:183], v230 offset:20480
	ds_read_b128 v[184:187], v230 offset:21504
	ds_read_b128 v[188:191], v230 offset:22528
	global_load_lds_dwordx4 v0, s[70:71]
	s_mov_b32 m0, s73
	ds_read_b128 v[192:195], v230 offset:23552
	global_load_lds_dwordx4 v2, s[70:71]
	s_barrier
	s_waitcnt lgkmcnt(0)
	v_mfma_f32_16x16x32_bf16 v[68:71], v[144:147], v[160:163], v[68:71]
	v_mfma_f32_16x16x32_bf16 v[64:67], v[152:155], v[160:163], v[64:67]
	v_mfma_f32_16x16x32_bf16 v[52:55], v[144:147], v[168:171], v[52:55]
	v_mfma_f32_16x16x32_bf16 v[48:51], v[152:155], v[168:171], v[48:51]
	v_mfma_f32_16x16x32_bf16 v[36:39], v[144:147], v[180:183], v[36:39]
	v_mfma_f32_16x16x32_bf16 v[32:35], v[152:155], v[180:183], v[32:35]
	v_mfma_f32_16x16x32_bf16 v[20:23], v[144:147], v[188:191], v[20:23]
	v_mfma_f32_16x16x32_bf16 v[16:19], v[152:155], v[188:191], v[16:19]
	v_mfma_f32_16x16x32_bf16 v[68:71], v[148:151], v[164:167], v[68:71]
	v_mfma_f32_16x16x32_bf16 v[64:67], v[156:159], v[164:167], v[64:67]
	v_mfma_f32_16x16x32_bf16 v[52:55], v[148:151], v[172:175], v[52:55]
	v_mfma_f32_16x16x32_bf16 v[48:51], v[156:159], v[172:175], v[48:51]
	v_mfma_f32_16x16x32_bf16 v[36:39], v[148:151], v[184:187], v[36:39]
	v_mfma_f32_16x16x32_bf16 v[32:35], v[156:159], v[184:187], v[32:35]
	v_mfma_f32_16x16x32_bf16 v[20:23], v[148:151], v[192:195], v[20:23]
	v_mfma_f32_16x16x32_bf16 v[16:19], v[156:159], v[192:195], v[16:19]
	s_add_i32 m0, s21, 0x14000
	s_add_u32 s64, s68, 0x40000
	s_addc_u32 s65, s69, 0
	s_barrier
	global_load_lds_dwordx4 v0, s[64:65]
	s_add_i32 m0, s21, 0x16000
	s_add_u32 s98, s70, 0x40000
	s_addc_u32 s99, s71, 0
	global_load_lds_dwordx4 v2, s[64:65]
	s_waitcnt vmcnt(6)
	s_barrier
; #define G_STAGE(bufoff, gbase) do { _Pragma("unroll") for (int _i = 0; _i < 2; ++_i) \
;         __builtin_amdgcn_global_load_lds((const unsigned*)((const char*)(gbase) + voff[_i]), (LAS unsigned*)(lds + (bufoff) + ldsw + _i * 8192), 16, 0, 0); } while (0)
; #define G_LDA(dst, b, h) do { _Pragma("unroll") for (int m = 0; m < 4; ++m) _Pragma("unroll") for (int k = 0; k < 2; ++k) dst[m][k] = *(const LAS bf16x8*)(lds + G_SA(b, h) + aoff + m * 2048 + k * 1024); } while (0)
; #define G_LDB(dst, b, h) do { _Pragma("unroll") for (int n = 0; n < 2; ++n) _Pragma("unroll") for (int k = 0; k < 2; ++k) dst[n][k] = *(const LAS bf16x8*)(lds + G_SB(b, h) + boff + n * 2048 + k * 1024); } while (0)
; #define G_MMA(ai, bj, At, Bt) do { __builtin_amdgcn_s_setprio(1); _Pragma("unroll") for (int m = 0; m < 4; ++m) _Pragma("unroll") for (int n = 0; n < 2; ++n) _Pragma("unroll") for (int k = 0; k < 2; ++k) \
;         acc[ai][bj][m][n] = MFMA16(Bt[n][k], At[m][k], acc[ai][bj][m][n]); __builtin_amdgcn_s_setprio(0); } while (0)
; #define G_WAIT_V(n) asm volatile("s_waitcnt vmcnt(" #n ")" ::: "memory")
; #define G_WAIT_L(n) asm volatile("s_waitcnt lgkmcnt(" #n ")" ::: "memory")
; #define G_BAR __builtin_amdgcn_s_barrier()
; #define G_SCHED __builtin_amdgcn_sched_barrier(0)
; template <class Epi>
; __device__ __forceinline__ void gemm_phase(LAS unsigned char* lds, const bf16_t* Ag, const bf16_t* Btg, const int K, const int nM, const int nN, const Epi& E) {
;     ...
;         for (int t = 0; t < nt; t += 2) {
;             const bool last = (t == nt - 2);
;             const char* a1 = cA + (size_t)(t + 1) * kstep;
;             const char* a2 = last ? nA : cA + (size_t)(t + 2) * kstep; const char* b2 = last ? nB : cB + (size_t)(t + 2) * kstep;
;             const char* a3 = a2 + kstep; const char* b3 = b2 + kstep;
;     ...
;             G_LDB(B0, 1, 0); G_SCHED; G_LDA(At, 1, 0); G_STAGE(G_SA(0, 1), a2 + hstep);
;             G_WAIT_L(8); G_BAR; G_WAIT_L(0); G_MMA(0, 0, At, B0); G_BAR; G_SCHED;
;             G_LDB(B1, 1, 1); G_STAGE(G_SB(1, 0), b3);
;             G_BAR; G_WAIT_L(0); G_MMA(0, 1, At, B1); G_BAR;
;             G_LDA(At, 1, 1); G_STAGE(G_SA(1, 0), a3);
;             G_BAR; G_WAIT_L(0); G_MMA(1, 0, At, B0); G_BAR; G_SCHED;
;             G_STAGE(G_SB(1, 1), b3 + hstep);
;             G_WAIT_V(6); G_BAR; G_MMA(1, 1, At, B1); G_BAR;
	v_mfma_f32_16x16x32_bf16 v[60:63], v[232:235], v[160:163], v[60:63]
	v_mfma_f32_16x16x32_bf16 v[56:59], v[240:243], v[160:163], v[56:59]
	v_mfma_f32_16x16x32_bf16 v[44:47], v[232:235], v[168:171], v[44:47]
	v_mfma_f32_16x16x32_bf16 v[40:43], v[240:243], v[168:171], v[40:43]
	v_mfma_f32_16x16x32_bf16 v[28:31], v[232:235], v[180:183], v[28:31]
	v_mfma_f32_16x16x32_bf16 v[24:27], v[240:243], v[180:183], v[24:27]
	v_mfma_f32_16x16x32_bf16 v[12:15], v[232:235], v[188:191], v[12:15]
	v_mfma_f32_16x16x32_bf16 v[8:11], v[240:243], v[188:191], v[8:11]
	v_mfma_f32_16x16x32_bf16 v[60:63], v[236:239], v[164:167], v[60:63]
	v_mfma_f32_16x16x32_bf16 v[56:59], v[244:247], v[164:167], v[56:59]
	v_mfma_f32_16x16x32_bf16 v[44:47], v[236:239], v[172:175], v[44:47]
	v_mfma_f32_16x16x32_bf16 v[40:43], v[244:247], v[172:175], v[40:43]
	v_mfma_f32_16x16x32_bf16 v[28:31], v[236:239], v[184:187], v[28:31]
	v_mfma_f32_16x16x32_bf16 v[24:27], v[244:247], v[184:187], v[24:27]
	v_mfma_f32_16x16x32_bf16 v[12:15], v[236:239], v[192:195], v[12:15]
	v_mfma_f32_16x16x32_bf16 v[8:11], v[244:247], v[192:195], v[8:11]
	s_mov_b32 m0, s74
	s_barrier
	ds_read_b128 v[144:147], v217 offset:32768
	ds_read_b128 v[148:151], v217 offset:33792
	ds_read_b128 v[152:155], v217 offset:34816
	ds_read_b128 v[156:159], v217 offset:35840
	ds_read_b128 v[160:163], v230 offset:32768
	ds_read_b128 v[164:167], v230 offset:33792
	ds_read_b128 v[168:171], v230 offset:34816
	ds_read_b128 v[172:175], v230 offset:35840
	ds_read_b128 v[180:183], v230 offset:36864
	ds_read_b128 v[184:187], v230 offset:37888
	ds_read_b128 v[188:191], v230 offset:38912
	global_load_lds_dwordx4 v0, s[98:99]
	s_mov_b32 m0, s75
	ds_read_b128 v[192:195], v230 offset:39936
	global_load_lds_dwordx4 v2, s[98:99]
	s_waitcnt lgkmcnt(8)
	s_barrier
	s_waitcnt lgkmcnt(0)
	v_mfma_f32_16x16x32_bf16 v[132:135], v[144:147], v[160:163], v[132:135]
	v_mfma_f32_16x16x32_bf16 v[128:131], v[152:155], v[160:163], v[128:131]
	v_mfma_f32_16x16x32_bf16 v[116:119], v[144:147], v[168:171], v[116:119]
	v_mfma_f32_16x16x32_bf16 v[112:115], v[152:155], v[168:171], v[112:115]
	v_mfma_f32_16x16x32_bf16 v[100:103], v[144:147], v[180:183], v[100:103]
	v_mfma_f32_16x16x32_bf16 v[96:99], v[152:155], v[180:183], v[96:99]
	v_mfma_f32_16x16x32_bf16 v[84:87], v[144:147], v[188:191], v[84:87]
	v_mfma_f32_16x16x32_bf16 v[80:83], v[152:155], v[188:191], v[80:83]
	v_mfma_f32_16x16x32_bf16 v[132:135], v[148:151], v[164:167], v[132:135]
	v_mfma_f32_16x16x32_bf16 v[128:131], v[156:159], v[164:167], v[128:131]
	v_mfma_f32_16x16x32_bf16 v[116:119], v[148:151], v[172:175], v[116:119]
	v_mfma_f32_16x16x32_bf16 v[112:115], v[156:159], v[172:175], v[112:115]
	v_mfma_f32_16x16x32_bf16 v[100:103], v[148:151], v[184:187], v[100:103]
	v_mfma_f32_16x16x32_bf16 v[96:99], v[156:159], v[184:187], v[96:99]
	v_mfma_f32_16x16x32_bf16 v[84:87], v[148:151], v[192:195], v[84:87]
	v_mfma_f32_16x16x32_bf16 v[80:83], v[156:159], v[192:195], v[80:83]
	s_add_i32 m0, s21, 0x18000
	s_add_u32 s98, s68, 0x80
	s_addc_u32 s99, s69, 0
	s_barrier
	ds_read_b128 v[232:235], v217 offset:49152
	ds_read_b128 v[236:239], v217 offset:50176
	ds_read_b128 v[240:243], v217 offset:51200
	global_load_lds_dwordx4 v0, s[98:99]
	s_add_i32 m0, s21, 0x1a000
	ds_read_b128 v[244:247], v217 offset:52224
	global_load_lds_dwordx4 v2, s[98:99]
	s_barrier
	s_waitcnt lgkmcnt(0)
	v_mfma_f32_16x16x32_bf16 v[124:127], v[232:235], v[160:163], v[124:127]
	v_mfma_f32_16x16x32_bf16 v[120:123], v[240:243], v[160:163], v[120:123]
	v_mfma_f32_16x16x32_bf16 v[108:111], v[232:235], v[168:171], v[108:111]
	v_mfma_f32_16x16x32_bf16 v[104:107], v[240:243], v[168:171], v[104:107]
	v_mfma_f32_16x16x32_bf16 v[92:95], v[232:235], v[180:183], v[92:95]
	v_mfma_f32_16x16x32_bf16 v[88:91], v[240:243], v[180:183], v[88:91]
	v_mfma_f32_16x16x32_bf16 v[76:79], v[232:235], v[188:191], v[76:79]
	v_mfma_f32_16x16x32_bf16 v[72:75], v[240:243], v[188:191], v[72:75]
	v_mfma_f32_16x16x32_bf16 v[124:127], v[236:239], v[164:167], v[124:127]
	v_mfma_f32_16x16x32_bf16 v[120:123], v[244:247], v[164:167], v[120:123]
	v_mfma_f32_16x16x32_bf16 v[108:111], v[236:239], v[172:175], v[108:111]
	v_mfma_f32_16x16x32_bf16 v[104:107], v[244:247], v[172:175], v[104:107]
	v_mfma_f32_16x16x32_bf16 v[92:95], v[236:239], v[184:187], v[92:95]
	v_mfma_f32_16x16x32_bf16 v[88:91], v[244:247], v[184:187], v[88:91]
	v_mfma_f32_16x16x32_bf16 v[76:79], v[236:239], v[192:195], v[76:79]
	v_mfma_f32_16x16x32_bf16 v[72:75], v[244:247], v[192:195], v[72:75]
	s_mov_b32 m0, s76
	s_add_u32 s98, s70, 0x80
	s_addc_u32 s99, s71, 0
	s_barrier
	ds_read_b128 v[160:163], v230 offset:49152
	ds_read_b128 v[164:167], v230 offset:50176
	ds_read_b128 v[168:171], v230 offset:51200
	ds_read_b128 v[172:175], v230 offset:52224
	ds_read_b128 v[180:183], v230 offset:53248
	ds_read_b128 v[184:187], v230 offset:54272
	ds_read_b128 v[188:191], v230 offset:55296
	global_load_lds_dwordx4 v0, s[98:99]
	s_mov_b32 m0, s77
	ds_read_b128 v[192:195], v230 offset:56320
	global_load_lds_dwordx4 v2, s[98:99]
	s_barrier
	s_waitcnt lgkmcnt(0)
	v_mfma_f32_16x16x32_bf16 v[68:71], v[144:147], v[160:163], v[68:71]
	v_mfma_f32_16x16x32_bf16 v[64:67], v[152:155], v[160:163], v[64:67]
	v_mfma_f32_16x16x32_bf16 v[52:55], v[144:147], v[168:171], v[52:55]
	v_mfma_f32_16x16x32_bf16 v[48:51], v[152:155], v[168:171], v[48:51]
	v_mfma_f32_16x16x32_bf16 v[36:39], v[144:147], v[180:183], v[36:39]
	v_mfma_f32_16x16x32_bf16 v[32:35], v[152:155], v[180:183], v[32:35]
	v_mfma_f32_16x16x32_bf16 v[20:23], v[144:147], v[188:191], v[20:23]
	v_mfma_f32_16x16x32_bf16 v[16:19], v[152:155], v[188:191], v[16:19]
	v_mfma_f32_16x16x32_bf16 v[68:71], v[148:151], v[164:167], v[68:71]
	v_mfma_f32_16x16x32_bf16 v[64:67], v[156:159], v[164:167], v[64:67]
	v_mfma_f32_16x16x32_bf16 v[52:55], v[148:151], v[172:175], v[52:55]
	v_mfma_f32_16x16x32_bf16 v[48:51], v[156:159], v[172:175], v[48:51]
	v_mfma_f32_16x16x32_bf16 v[36:39], v[148:151], v[184:187], v[36:39]
	v_mfma_f32_16x16x32_bf16 v[32:35], v[156:159], v[184:187], v[32:35]
	v_mfma_f32_16x16x32_bf16 v[20:23], v[148:151], v[192:195], v[20:23]
	v_mfma_f32_16x16x32_bf16 v[16:19], v[156:159], v[192:195], v[16:19]
	s_add_i32 m0, s21, 0x1c000
	s_add_u32 s64, s68, 0x40080
	s_addc_u32 s65, s69, 0
	s_barrier
	global_load_lds_dwordx4 v0, s[64:65]
	s_add_i32 m0, s21, 0x1e000
	s_add_i32 s42, s42, 2
	global_load_lds_dwordx4 v2, s[64:65]
	s_add_u32 s57, s57, 0x100
	s_addc_u32 s61, s61, 0
	s_mov_b64 s[64:65], s[66:67]
	s_cmp_gt_u32 s42, 13
	s_cbranch_scc1 .LrotX_153
	s_add_u32 s66, s64, 0x100
	s_addc_u32 s67, s65, 0
	s_cmp_lg_u32 s42, 12
	s_cselect_b32 s71, s67, s55
	s_cselect_b32 s70, s66, s54
	s_cselect_b32 s69, s61, s14
	s_cselect_b32 s68, s57, s15
; #define G_STAGE(bufoff, gbase) do { _Pragma("unroll") for (int _i = 0; _i < 2; ++_i) \
;         __builtin_amdgcn_global_load_lds((const unsigned*)((const char*)(gbase) + voff[_i]), (LAS unsigned*)(lds + (bufoff) + ldsw + _i * 8192), 16, 0, 0); } while (0)
; #define G_MMA(ai, bj, At, Bt) do { __builtin_amdgcn_s_setprio(1); _Pragma("unroll") for (int m = 0; m < 4; ++m) _Pragma("unroll") for (int n = 0; n < 2; ++n) _Pragma("unroll") for (int k = 0; k < 2; ++k) \
;         acc[ai][bj][m][n] = MFMA16(Bt[n][k], At[m][k], acc[ai][bj][m][n]); __builtin_amdgcn_s_setprio(0); } while (0)
; #define G_WAIT_V(n) asm volatile("s_waitcnt vmcnt(" #n ")" ::: "memory")
; #define G_BAR __builtin_amdgcn_s_barrier()
; template <class Epi>
; __device__ __forceinline__ void gemm_phase(LAS unsigned char* lds, const bf16_t* Ag, const bf16_t* Btg, const int K, const int nM, const int nN, const Epi& E) {
;     ...
;             G_STAGE(G_SB(1, 1), b3 + hstep);
;             G_WAIT_V(6); G_BAR; G_MMA(1, 1, At, B1); G_BAR;
;         }
.LrotX_153:
	s_waitcnt vmcnt(6)
	s_barrier
	v_mfma_f32_16x16x32_bf16 v[60:63], v[232:235], v[160:163], v[60:63]
	v_mfma_f32_16x16x32_bf16 v[56:59], v[240:243], v[160:163], v[56:59]
	v_mfma_f32_16x16x32_bf16 v[44:47], v[232:235], v[168:171], v[44:47]
	v_mfma_f32_16x16x32_bf16 v[40:43], v[240:243], v[168:171], v[40:43]
	v_mfma_f32_16x16x32_bf16 v[28:31], v[232:235], v[180:183], v[28:31]
	v_mfma_f32_16x16x32_bf16 v[24:27], v[240:243], v[180:183], v[24:27]
	v_mfma_f32_16x16x32_bf16 v[12:15], v[232:235], v[188:191], v[12:15]
	v_mfma_f32_16x16x32_bf16 v[8:11], v[240:243], v[188:191], v[8:11]
	v_mfma_f32_16x16x32_bf16 v[60:63], v[236:239], v[164:167], v[60:63]
	v_mfma_f32_16x16x32_bf16 v[56:59], v[244:247], v[164:167], v[56:59]
	v_mfma_f32_16x16x32_bf16 v[44:47], v[236:239], v[172:175], v[44:47]
	v_mfma_f32_16x16x32_bf16 v[40:43], v[244:247], v[172:175], v[40:43]
	v_mfma_f32_16x16x32_bf16 v[28:31], v[236:239], v[184:187], v[28:31]
	v_mfma_f32_16x16x32_bf16 v[24:27], v[244:247], v[184:187], v[24:27]
	v_mfma_f32_16x16x32_bf16 v[12:15], v[236:239], v[192:195], v[12:15]
	v_mfma_f32_16x16x32_bf16 v[8:11], v[244:247], v[192:195], v[8:11]
	s_add_i32 m0, s72, 0xc000
	s_cmp_lt_u32 s42, 12
	s_barrier
	s_cbranch_scc1 .LmainW_153
	s_cmp_gt_u32 s42, 13
	s_cbranch_scc1 .LBB0_157

;     __device__ __forceinline__ void prep(int pm, int par, LAS unsigned char* lds) const { if (fold) prep_rowstats(stat, pm, par, lds); }
;     __device__ __forceinline__ void prep(int pm, int par, LAS unsigned char* lds) const { if (!ident) prep_rowstats(stat, pm, par, lds); }
;     __device__ __forceinline__ void prep(int pm, int par, LAS unsigned char* lds) const { prep_rowstats(stat, pm, par, lds); }
; #define G_STAGE(bufoff, gbase) do { _Pragma("unroll") for (int _i = 0; _i < 2; ++_i) \
;         __builtin_amdgcn_global_load_lds((const unsigned*)((const char*)(gbase) + voff[_i]), (LAS unsigned*)(lds + (bufoff) + ldsw + _i * 8192), 16, 0, 0); } while (0)
; #define G_LDA(dst, b, h) do { _Pragma("unroll") for (int m = 0; m < 4; ++m) _Pragma("unroll") for (int k = 0; k < 2; ++k) dst[m][k] = *(const LAS bf16x8*)(lds + G_SA(b, h) + aoff + m * 2048 + k * 1024); } while (0)
; #define G_LDB(dst, b, h) do { _Pragma("unroll") for (int n = 0; n < 2; ++n) _Pragma("unroll") for (int k = 0; k < 2; ++k) dst[n][k] = *(const LAS bf16x8*)(lds + G_SB(b, h) + boff + n * 2048 + k * 1024); } while (0)
; #define G_WAIT_V(n) asm volatile("s_waitcnt vmcnt(" #n ")" ::: "memory")
; #define G_WAIT_L(n) asm volatile("s_waitcnt lgkmcnt(" #n ")" ::: "memory")
; #define G_BAR __builtin_amdgcn_s_barrier()
; #define G_SCHED __builtin_amdgcn_sched_barrier(0)
; template <class Epi>
; __device__ __forceinline__ void gemm_phase(LAS unsigned char* lds, const bf16_t* Ag, const bf16_t* Btg, const int K, const int nM, const int nN, const Epi& E) {
;     ...
;             const char* a2 = last ? nA : cA + (size_t)(t + 2) * kstep; const char* b2 = last ? nB : cB + (size_t)(t + 2) * kstep;
;             const char* a3 = a2 + kstep; const char* b3 = b2 + kstep;
;             if (last && has_next && pmn != pm) E.prep(pmn, par ^ 1, lds);
;             G_LDB(B0, 0, 0); G_SCHED; G_LDA(At, 0, 0); G_STAGE(G_SA(1, 1), a1 + hstep);
;             G_WAIT_L(8); G_BAR; G_WAIT_L(0); G_MMA(0, 0, At, B0); G_BAR; G_SCHED;
;             G_LDB(B1, 0, 1); G_STAGE(G_SB(0, 0), b2);
;             G_BAR; G_WAIT_L(0); G_MMA(0, 1, At, B1); G_BAR;
;             G_LDA(At, 0, 1); G_STAGE(G_SA(0, 0), a2);
;             G_BAR; G_WAIT_L(0); G_MMA(1, 0, At, B0); G_BAR; G_SCHED;
;             G_STAGE(G_SB(0, 1), b2 + hstep);
;             G_WAIT_V(6); G_BAR; G_MMA(1, 1, At, B1); G_BAR;
.LBB0_744:
	s_add_u32 s58, s56, 0x100
	s_addc_u32 s59, s57, 0
	s_and_b64 s[60:61], s[60:61], exec
	s_cselect_b32 s63, s59, s47
	s_cselect_b32 s62, s58, s46
	s_cselect_b32 s61, s78, s15
	s_cselect_b32 s60, s77, s49
	s_add_i32 m0, s66, 0xc000
.LmainW_744:
	ds_read_b128 v[140:143], v217
	ds_read_b128 v[144:147], v217 offset:1024
	ds_read_b128 v[148:151], v217 offset:2048
	ds_read_b128 v[152:155], v217 offset:3072
	ds_read_b128 v[156:159], v174
	ds_read_b128 v[160:163], v174 offset:1024
	ds_read_b128 v[180:183], v174 offset:2048
	ds_read_b128 v[184:187], v174 offset:3072
	ds_read_b128 v[188:191], v174 offset:4096
	ds_read_b128 v[192:195], v174 offset:5120
	ds_read_b128 v[222:225], v174 offset:6144
	global_load_lds_dwordx4 v138, s[56:57]
	s_add_i32 m0, s66, 0xe000
	ds_read_b128 v[226:229], v174 offset:7168
	global_load_lds_dwordx4 v136, s[56:57]
	s_waitcnt lgkmcnt(8)
	s_barrier
	s_waitcnt lgkmcnt(0)
	v_mfma_f32_16x16x32_bf16 v[132:135], v[140:143], v[156:159], v[132:135]
	v_mfma_f32_16x16x32_bf16 v[128:131], v[148:151], v[156:159], v[128:131]
	v_mfma_f32_16x16x32_bf16 v[116:119], v[140:143], v[180:183], v[116:119]
	v_mfma_f32_16x16x32_bf16 v[112:115], v[148:151], v[180:183], v[112:115]
	v_mfma_f32_16x16x32_bf16 v[100:103], v[140:143], v[188:191], v[100:103]
	v_mfma_f32_16x16x32_bf16 v[96:99], v[148:151], v[188:191], v[96:99]
	v_mfma_f32_16x16x32_bf16 v[84:87], v[140:143], v[222:225], v[84:87]
	v_mfma_f32_16x16x32_bf16 v[80:83], v[148:151], v[222:225], v[80:83]
	v_mfma_f32_16x16x32_bf16 v[132:135], v[144:147], v[160:163], v[132:135]
	v_mfma_f32_16x16x32_bf16 v[128:131], v[152:155], v[160:163], v[128:131]
	v_mfma_f32_16x16x32_bf16 v[116:119], v[144:147], v[184:187], v[116:119]
	v_mfma_f32_16x16x32_bf16 v[112:115], v[152:155], v[184:187], v[112:115]
	v_mfma_f32_16x16x32_bf16 v[100:103], v[144:147], v[192:195], v[100:103]
	v_mfma_f32_16x16x32_bf16 v[96:99], v[152:155], v[192:195], v[96:99]
	v_mfma_f32_16x16x32_bf16 v[84:87], v[144:147], v[226:229], v[84:87]
	v_mfma_f32_16x16x32_bf16 v[80:83], v[152:155], v[226:229], v[80:83]
	s_add_i32 m0, s65, 0x10000
	s_barrier
	ds_read_b128 v[230:233], v217 offset:16384
	ds_read_b128 v[234:237], v217 offset:17408
	ds_read_b128 v[238:241], v217 offset:18432
	global_load_lds_dwordx4 v0, s[60:61]
	s_add_i32 m0, s65, 0x12000
	ds_read_b128 v[242:245], v217 offset:19456
	global_load_lds_dwordx4 v2, s[60:61]
	s_barrier
	s_waitcnt lgkmcnt(0)
	v_mfma_f32_16x16x32_bf16 v[124:127], v[230:233], v[156:159], v[124:127]
	v_mfma_f32_16x16x32_bf16 v[120:123], v[238:241], v[156:159], v[120:123]
	v_mfma_f32_16x16x32_bf16 v[108:111], v[230:233], v[180:183], v[108:111]
	v_mfma_f32_16x16x32_bf16 v[104:107], v[238:241], v[180:183], v[104:107]
	v_mfma_f32_16x16x32_bf16 v[92:95], v[230:233], v[188:191], v[92:95]
	v_mfma_f32_16x16x32_bf16 v[88:91], v[238:241], v[188:191], v[88:91]
	v_mfma_f32_16x16x32_bf16 v[76:79], v[230:233], v[222:225], v[76:79]
	v_mfma_f32_16x16x32_bf16 v[72:75], v[238:241], v[222:225], v[72:75]
	v_mfma_f32_16x16x32_bf16 v[124:127], v[234:237], v[160:163], v[124:127]
	v_mfma_f32_16x16x32_bf16 v[120:123], v[242:245], v[160:163], v[120:123]
	v_mfma_f32_16x16x32_bf16 v[108:111], v[234:237], v[184:187], v[108:111]
	v_mfma_f32_16x16x32_bf16 v[104:107], v[242:245], v[184:187], v[104:107]
	v_mfma_f32_16x16x32_bf16 v[92:95], v[234:237], v[192:195], v[92:95]
	v_mfma_f32_16x16x32_bf16 v[88:91], v[242:245], v[192:195], v[88:91]
	v_mfma_f32_16x16x32_bf16 v[76:79], v[234:237], v[226:229], v[76:79]
	v_mfma_f32_16x16x32_bf16 v[72:75], v[242:245], v[226:229], v[72:75]
	s_mov_b32 m0, s66
	s_barrier
	ds_read_b128 v[156:159], v174 offset:16384
	ds_read_b128 v[160:163], v174 offset:17408
	ds_read_b128 v[180:183], v174 offset:18432
	ds_read_b128 v[184:187], v174 offset:19456
	ds_read_b128 v[188:191], v174 offset:20480
	ds_read_b128 v[192:195], v174 offset:21504
	ds_read_b128 v[222:225], v174 offset:22528
	global_load_lds_dwordx4 v0, s[62:63]
	s_mov_b32 m0, s67
	ds_read_b128 v[226:229], v174 offset:23552
	global_load_lds_dwordx4 v2, s[62:63]
	s_barrier
	s_waitcnt lgkmcnt(0)
	v_mfma_f32_16x16x32_bf16 v[68:71], v[140:143], v[156:159], v[68:71]
	v_mfma_f32_16x16x32_bf16 v[64:67], v[148:151], v[156:159], v[64:67]
	v_mfma_f32_16x16x32_bf16 v[52:55], v[140:143], v[180:183], v[52:55]
	v_mfma_f32_16x16x32_bf16 v[48:51], v[148:151], v[180:183], v[48:51]
	v_mfma_f32_16x16x32_bf16 v[36:39], v[140:143], v[188:191], v[36:39]
	v_mfma_f32_16x16x32_bf16 v[32:35], v[148:151], v[188:191], v[32:35]
	v_mfma_f32_16x16x32_bf16 v[20:23], v[140:143], v[222:225], v[20:23]
	v_mfma_f32_16x16x32_bf16 v[16:19], v[148:151], v[222:225], v[16:19]
	v_mfma_f32_16x16x32_bf16 v[68:71], v[144:147], v[160:163], v[68:71]
	v_mfma_f32_16x16x32_bf16 v[64:67], v[152:155], v[160:163], v[64:67]
	v_mfma_f32_16x16x32_bf16 v[52:55], v[144:147], v[184:187], v[52:55]
	v_mfma_f32_16x16x32_bf16 v[48:51], v[152:155], v[184:187], v[48:51]
	v_mfma_f32_16x16x32_bf16 v[36:39], v[144:147], v[192:195], v[36:39]
	v_mfma_f32_16x16x32_bf16 v[32:35], v[152:155], v[192:195], v[32:35]
	v_mfma_f32_16x16x32_bf16 v[20:23], v[144:147], v[226:229], v[20:23]
	v_mfma_f32_16x16x32_bf16 v[16:19], v[152:155], v[226:229], v[16:19]
	s_add_i32 m0, s65, 0x14000
	s_add_u32 s56, s60, 0x100000
	s_addc_u32 s57, s61, 0
	s_barrier
	global_load_lds_dwordx4 v0, s[56:57]
	s_add_i32 m0, s65, 0x16000
	s_add_u32 s98, s62, 0x100000
	s_addc_u32 s99, s63, 0
	global_load_lds_dwordx4 v2, s[56:57]
	s_waitcnt vmcnt(6)
	s_barrier
; #define G_STAGE(bufoff, gbase) do { _Pragma("unroll") for (int _i = 0; _i < 2; ++_i) \
;         __builtin_amdgcn_global_load_lds((const unsigned*)((const char*)(gbase) + voff[_i]), (LAS unsigned*)(lds + (bufoff) + ldsw + _i * 8192), 16, 0, 0); } while (0)
; #define G_LDA(dst, b, h) do { _Pragma("unroll") for (int m = 0; m < 4; ++m) _Pragma("unroll") for (int k = 0; k < 2; ++k) dst[m][k] = *(const LAS bf16x8*)(lds + G_SA(b, h) + aoff + m * 2048 + k * 1024); } while (0)
; #define G_LDB(dst, b, h) do { _Pragma("unroll") for (int n = 0; n < 2; ++n) _Pragma("unroll") for (int k = 0; k < 2; ++k) dst[n][k] = *(const LAS bf16x8*)(lds + G_SB(b, h) + boff + n * 2048 + k * 1024); } while (0)
; #define G_MMA(ai, bj, At, Bt) do { __builtin_amdgcn_s_setprio(1); _Pragma("unroll") for (int m = 0; m < 4; ++m) _Pragma("unroll") for (int n = 0; n < 2; ++n) _Pragma("unroll") for (int k = 0; k < 2; ++k) \
;         acc[ai][bj][m][n] = MFMA16(Bt[n][k], At[m][k], acc[ai][bj][m][n]); __builtin_amdgcn_s_setprio(0); } while (0)
; #define G_WAIT_V(n) asm volatile("s_waitcnt vmcnt(" #n ")" ::: "memory")
; #define G_WAIT_L(n) asm volatile("s_waitcnt lgkmcnt(" #n ")" ::: "memory")
; #define G_BAR __builtin_amdgcn_s_barrier()
; #define G_SCHED __builtin_amdgcn_sched_barrier(0)
; template <class Epi>
; __device__ __forceinline__ void gemm_phase(LAS unsigned char* lds, const bf16_t* Ag, const bf16_t* Btg, const int K, const int nM, const int nN, const Epi& E) {
;     ...
;         for (int t = 0; t < nt; t += 2) {
;             const bool last = (t == nt - 2);
;             const char* a1 = cA + (size_t)(t + 1) * kstep;
;             const char* a2 = last ? nA : cA + (size_t)(t + 2) * kstep; const char* b2 = last ? nB : cB + (size_t)(t + 2) * kstep;
;             const char* a3 = a2 + kstep; const char* b3 = b2 + kstep;
;     ...
;             G_LDB(B0, 1, 0); G_SCHED; G_LDA(At, 1, 0); G_STAGE(G_SA(0, 1), a2 + hstep);
;             G_WAIT_L(8); G_BAR; G_WAIT_L(0); G_MMA(0, 0, At, B0); G_BAR; G_SCHED;
;             G_LDB(B1, 1, 1); G_STAGE(G_SB(1, 0), b3);
;             G_BAR; G_WAIT_L(0); G_MMA(0, 1, At, B1); G_BAR;
;             G_LDA(At, 1, 1); G_STAGE(G_SA(1, 0), a3);
;             G_BAR; G_WAIT_L(0); G_MMA(1, 0, At, B0); G_BAR; G_SCHED;
;             G_STAGE(G_SB(1, 1), b3 + hstep);
;             G_WAIT_V(6); G_BAR; G_MMA(1, 1, At, B1); G_BAR;
	v_mfma_f32_16x16x32_bf16 v[60:63], v[230:233], v[156:159], v[60:63]
	v_mfma_f32_16x16x32_bf16 v[56:59], v[238:241], v[156:159], v[56:59]
	v_mfma_f32_16x16x32_bf16 v[44:47], v[230:233], v[180:183], v[44:47]
	v_mfma_f32_16x16x32_bf16 v[40:43], v[238:241], v[180:183], v[40:43]
	v_mfma_f32_16x16x32_bf16 v[28:31], v[230:233], v[188:191], v[28:31]
	v_mfma_f32_16x16x32_bf16 v[24:27], v[238:241], v[188:191], v[24:27]
	v_mfma_f32_16x16x32_bf16 v[12:15], v[230:233], v[222:225], v[12:15]
	v_mfma_f32_16x16x32_bf16 v[8:11], v[238:241], v[222:225], v[8:11]
	v_mfma_f32_16x16x32_bf16 v[60:63], v[234:237], v[160:163], v[60:63]
	v_mfma_f32_16x16x32_bf16 v[56:59], v[242:245], v[160:163], v[56:59]
	v_mfma_f32_16x16x32_bf16 v[44:47], v[234:237], v[184:187], v[44:47]
	v_mfma_f32_16x16x32_bf16 v[40:43], v[242:245], v[184:187], v[40:43]
	v_mfma_f32_16x16x32_bf16 v[28:31], v[234:237], v[192:195], v[28:31]
	v_mfma_f32_16x16x32_bf16 v[24:27], v[242:245], v[192:195], v[24:27]
	v_mfma_f32_16x16x32_bf16 v[12:15], v[234:237], v[226:229], v[12:15]
	v_mfma_f32_16x16x32_bf16 v[8:11], v[242:245], v[226:229], v[8:11]
	s_mov_b32 m0, s68
	s_barrier
	ds_read_b128 v[140:143], v217 offset:32768
	ds_read_b128 v[144:147], v217 offset:33792
	ds_read_b128 v[148:151], v217 offset:34816
	ds_read_b128 v[152:155], v217 offset:35840
	ds_read_b128 v[156:159], v174 offset:32768
	ds_read_b128 v[160:163], v174 offset:33792
	ds_read_b128 v[180:183], v174 offset:34816
	ds_read_b128 v[184:187], v174 offset:35840
	ds_read_b128 v[188:191], v174 offset:36864
	ds_read_b128 v[192:195], v174 offset:37888
	ds_read_b128 v[222:225], v174 offset:38912
	global_load_lds_dwordx4 v0, s[98:99]
	s_mov_b32 m0, s69
	ds_read_b128 v[226:229], v174 offset:39936
	global_load_lds_dwordx4 v2, s[98:99]
	s_waitcnt lgkmcnt(8)
	s_barrier
	s_waitcnt lgkmcnt(0)
	v_mfma_f32_16x16x32_bf16 v[132:135], v[140:143], v[156:159], v[132:135]
	v_mfma_f32_16x16x32_bf16 v[128:131], v[148:151], v[156:159], v[128:131]
	v_mfma_f32_16x16x32_bf16 v[116:119], v[140:143], v[180:183], v[116:119]
	v_mfma_f32_16x16x32_bf16 v[112:115], v[148:151], v[180:183], v[112:115]
	v_mfma_f32_16x16x32_bf16 v[100:103], v[140:143], v[188:191], v[100:103]
	v_mfma_f32_16x16x32_bf16 v[96:99], v[148:151], v[188:191], v[96:99]
	v_mfma_f32_16x16x32_bf16 v[84:87], v[140:143], v[222:225], v[84:87]
	v_mfma_f32_16x16x32_bf16 v[80:83], v[148:151], v[222:225], v[80:83]
	v_mfma_f32_16x16x32_bf16 v[132:135], v[144:147], v[160:163], v[132:135]
	v_mfma_f32_16x16x32_bf16 v[128:131], v[152:155], v[160:163], v[128:131]
	v_mfma_f32_16x16x32_bf16 v[116:119], v[144:147], v[184:187], v[116:119]
	v_mfma_f32_16x16x32_bf16 v[112:115], v[152:155], v[184:187], v[112:115]
	v_mfma_f32_16x16x32_bf16 v[100:103], v[144:147], v[192:195], v[100:103]
	v_mfma_f32_16x16x32_bf16 v[96:99], v[152:155], v[192:195], v[96:99]
	v_mfma_f32_16x16x32_bf16 v[84:87], v[144:147], v[226:229], v[84:87]
	v_mfma_f32_16x16x32_bf16 v[80:83], v[152:155], v[226:229], v[80:83]
	s_add_i32 m0, s65, 0x18000
	s_add_u32 s98, s60, 0x80
	s_addc_u32 s99, s61, 0
	s_barrier
	ds_read_b128 v[230:233], v217 offset:49152
	ds_read_b128 v[234:237], v217 offset:50176
	ds_read_b128 v[238:241], v217 offset:51200
	global_load_lds_dwordx4 v0, s[98:99]
	s_add_i32 m0, s65, 0x1a000
	ds_read_b128 v[242:245], v217 offset:52224
	global_load_lds_dwordx4 v2, s[98:99]
	s_barrier
	s_waitcnt lgkmcnt(0)
	v_mfma_f32_16x16x32_bf16 v[124:127], v[230:233], v[156:159], v[124:127]
	v_mfma_f32_16x16x32_bf16 v[120:123], v[238:241], v[156:159], v[120:123]
	v_mfma_f32_16x16x32_bf16 v[108:111], v[230:233], v[180:183], v[108:111]
	v_mfma_f32_16x16x32_bf16 v[104:107], v[238:241], v[180:183], v[104:107]
	v_mfma_f32_16x16x32_bf16 v[92:95], v[230:233], v[188:191], v[92:95]
	v_mfma_f32_16x16x32_bf16 v[88:91], v[238:241], v[188:191], v[88:91]
	v_mfma_f32_16x16x32_bf16 v[76:79], v[230:233], v[222:225], v[76:79]
	v_mfma_f32_16x16x32_bf16 v[72:75], v[238:241], v[222:225], v[72:75]
	v_mfma_f32_16x16x32_bf16 v[124:127], v[234:237], v[160:163], v[124:127]
	v_mfma_f32_16x16x32_bf16 v[120:123], v[242:245], v[160:163], v[120:123]
	v_mfma_f32_16x16x32_bf16 v[108:111], v[234:237], v[184:187], v[108:111]
	v_mfma_f32_16x16x32_bf16 v[104:107], v[242:245], v[184:187], v[104:107]
	v_mfma_f32_16x16x32_bf16 v[92:95], v[234:237], v[192:195], v[92:95]
	v_mfma_f32_16x16x32_bf16 v[88:91], v[242:245], v[192:195], v[88:91]
	v_mfma_f32_16x16x32_bf16 v[76:79], v[234:237], v[226:229], v[76:79]
	v_mfma_f32_16x16x32_bf16 v[72:75], v[242:245], v[226:229], v[72:75]
	s_mov_b32 m0, s70
	s_add_u32 s98, s62, 0x80
	s_addc_u32 s99, s63, 0
	s_barrier
	ds_read_b128 v[156:159], v174 offset:49152
	ds_read_b128 v[160:163], v174 offset:50176
	ds_read_b128 v[180:183], v174 offset:51200
	ds_read_b128 v[184:187], v174 offset:52224
	ds_read_b128 v[188:191], v174 offset:53248
	ds_read_b128 v[192:195], v174 offset:54272
	ds_read_b128 v[222:225], v174 offset:55296
	global_load_lds_dwordx4 v0, s[98:99]
	s_mov_b32 m0, s71
	ds_read_b128 v[226:229], v174 offset:56320
	global_load_lds_dwordx4 v2, s[98:99]
	s_barrier
	s_waitcnt lgkmcnt(0)
	v_mfma_f32_16x16x32_bf16 v[68:71], v[140:143], v[156:159], v[68:71]
	v_mfma_f32_16x16x32_bf16 v[64:67], v[148:151], v[156:159], v[64:67]
	v_mfma_f32_16x16x32_bf16 v[52:55], v[140:143], v[180:183], v[52:55]
	v_mfma_f32_16x16x32_bf16 v[48:51], v[148:151], v[180:183], v[48:51]
	v_mfma_f32_16x16x32_bf16 v[36:39], v[140:143], v[188:191], v[36:39]
	v_mfma_f32_16x16x32_bf16 v[32:35], v[148:151], v[188:191], v[32:35]
	v_mfma_f32_16x16x32_bf16 v[20:23], v[140:143], v[222:225], v[20:23]
	v_mfma_f32_16x16x32_bf16 v[16:19], v[148:151], v[222:225], v[16:19]
	v_mfma_f32_16x16x32_bf16 v[68:71], v[144:147], v[160:163], v[68:71]
	v_mfma_f32_16x16x32_bf16 v[64:67], v[152:155], v[160:163], v[64:67]
	v_mfma_f32_16x16x32_bf16 v[52:55], v[144:147], v[184:187], v[52:55]
	v_mfma_f32_16x16x32_bf16 v[48:51], v[152:155], v[184:187], v[48:51]
	v_mfma_f32_16x16x32_bf16 v[36:39], v[144:147], v[192:195], v[36:39]
	v_mfma_f32_16x16x32_bf16 v[32:35], v[152:155], v[192:195], v[32:35]
	v_mfma_f32_16x16x32_bf16 v[20:23], v[144:147], v[226:229], v[20:23]
	v_mfma_f32_16x16x32_bf16 v[16:19], v[152:155], v[226:229], v[16:19]
	s_add_i32 m0, s65, 0x1c000
	s_add_u32 s56, s60, 0x100080
	s_addc_u32 s57, s61, 0
	s_barrier
	global_load_lds_dwordx4 v0, s[56:57]
	s_add_i32 m0, s65, 0x1e000
	s_add_i32 s79, s79, 2
	global_load_lds_dwordx4 v2, s[56:57]
	s_add_u32 s77, s77, 0x100
	s_addc_u32 s78, s78, 0
	s_mov_b64 s[56:57], s[58:59]
	s_cmp_gt_u32 s79, 61
	s_cbranch_scc1 .LrotX_744
	s_add_u32 s58, s56, 0x100
	s_addc_u32 s59, s57, 0
	s_cmp_lg_u32 s79, 60
	s_cselect_b32 s63, s59, s47
	s_cselect_b32 s62, s58, s46
	s_cselect_b32 s61, s78, s15
	s_cselect_b32 s60, s77, s49
; #define G_STAGE(bufoff, gbase) do { _Pragma("unroll") for (int _i = 0; _i < 2; ++_i) \
;         __builtin_amdgcn_global_load_lds((const unsigned*)((const char*)(gbase) + voff[_i]), (LAS unsigned*)(lds + (bufoff) + ldsw + _i * 8192), 16, 0, 0); } while (0)
; #define G_MMA(ai, bj, At, Bt) do { __builtin_amdgcn_s_setprio(1); _Pragma("unroll") for (int m = 0; m < 4; ++m) _Pragma("unroll") for (int n = 0; n < 2; ++n) _Pragma("unroll") for (int k = 0; k < 2; ++k) \
;         acc[ai][bj][m][n] = MFMA16(Bt[n][k], At[m][k], acc[ai][bj][m][n]); __builtin_amdgcn_s_setprio(0); } while (0)
; #define G_WAIT_V(n) asm volatile("s_waitcnt vmcnt(" #n ")" ::: "memory")
; #define G_BAR __builtin_amdgcn_s_barrier()
; template <class Epi>
; __device__ __forceinline__ void gemm_phase(LAS unsigned char* lds, const bf16_t* Ag, const bf16_t* Btg, const int K, const int nM, const int nN, const Epi& E) {
;     ...
;             G_STAGE(G_SB(1, 1), b3 + hstep);
;             G_WAIT_V(6); G_BAR; G_MMA(1, 1, At, B1); G_BAR;
;         }
.LrotX_744:
	s_waitcnt vmcnt(6)
	s_barrier
	v_mfma_f32_16x16x32_bf16 v[60:63], v[230:233], v[156:159], v[60:63]
	v_mfma_f32_16x16x32_bf16 v[56:59], v[238:241], v[156:159], v[56:59]
	v_mfma_f32_16x16x32_bf16 v[44:47], v[230:233], v[180:183], v[44:47]
	v_mfma_f32_16x16x32_bf16 v[40:43], v[238:241], v[180:183], v[40:43]
	v_mfma_f32_16x16x32_bf16 v[28:31], v[230:233], v[188:191], v[28:31]
	v_mfma_f32_16x16x32_bf16 v[24:27], v[238:241], v[188:191], v[24:27]
	v_mfma_f32_16x16x32_bf16 v[12:15], v[230:233], v[222:225], v[12:15]
	v_mfma_f32_16x16x32_bf16 v[8:11], v[238:241], v[222:225], v[8:11]
	v_mfma_f32_16x16x32_bf16 v[60:63], v[234:237], v[160:163], v[60:63]
	v_mfma_f32_16x16x32_bf16 v[56:59], v[242:245], v[160:163], v[56:59]
	v_mfma_f32_16x16x32_bf16 v[44:47], v[234:237], v[184:187], v[44:47]
	v_mfma_f32_16x16x32_bf16 v[40:43], v[242:245], v[184:187], v[40:43]
	v_mfma_f32_16x16x32_bf16 v[28:31], v[234:237], v[192:195], v[28:31]
	v_mfma_f32_16x16x32_bf16 v[24:27], v[242:245], v[192:195], v[24:27]
	v_mfma_f32_16x16x32_bf16 v[12:15], v[234:237], v[226:229], v[12:15]
	v_mfma_f32_16x16x32_bf16 v[8:11], v[242:245], v[226:229], v[8:11]
	s_add_i32 m0, s66, 0xc000
	s_cmp_lt_u32 s79, 60
	s_barrier
	s_cbranch_scc1 .LmainW_744
	s_cmp_gt_u32 s79, 61
	s_cbranch_scc1 .LBB0_748

;     __device__ __forceinline__ void prep(int pm, int par, LAS unsigned char* lds) const { if (fold) prep_rowstats(stat, pm, par, lds); }
;     __device__ __forceinline__ void prep(int pm, int par, LAS unsigned char* lds) const { if (!ident) prep_rowstats(stat, pm, par, lds); }
;     __device__ __forceinline__ void prep(int pm, int par, LAS unsigned char* lds) const { prep_rowstats(stat, pm, par, lds); }
; #define G_STAGE(bufoff, gbase) do { _Pragma("unroll") for (int _i = 0; _i < 2; ++_i) \
;         __builtin_amdgcn_global_load_lds((const unsigned*)((const char*)(gbase) + voff[_i]), (LAS unsigned*)(lds + (bufoff) + ldsw + _i * 8192), 16, 0, 0); } while (0)
; #define G_LDA(dst, b, h) do { _Pragma("unroll") for (int m = 0; m < 4; ++m) _Pragma("unroll") for (int k = 0; k < 2; ++k) dst[m][k] = *(const LAS bf16x8*)(lds + G_SA(b, h) + aoff + m * 2048 + k * 1024); } while (0)
; #define G_LDB(dst, b, h) do { _Pragma("unroll") for (int n = 0; n < 2; ++n) _Pragma("unroll") for (int k = 0; k < 2; ++k) dst[n][k] = *(const LAS bf16x8*)(lds + G_SB(b, h) + boff + n * 2048 + k * 1024); } while (0)
; #define G_WAIT_V(n) asm volatile("s_waitcnt vmcnt(" #n ")" ::: "memory")
; #define G_WAIT_L(n) asm volatile("s_waitcnt lgkmcnt(" #n ")" ::: "memory")
; #define G_BAR __builtin_amdgcn_s_barrier()
; #define G_SCHED __builtin_amdgcn_sched_barrier(0)
; template <class Epi>
; __device__ __forceinline__ void gemm_phase(LAS unsigned char* lds, const bf16_t* Ag, const bf16_t* Btg, const int K, const int nM, const int nN, const Epi& E) {
;     ...
;             const char* a2 = last ? nA : cA + (size_t)(t + 2) * kstep; const char* b2 = last ? nB : cB + (size_t)(t + 2) * kstep;
;             const char* a3 = a2 + kstep; const char* b3 = b2 + kstep;
;             if (last && has_next && pmn != pm) E.prep(pmn, par ^ 1, lds);
;             G_LDB(B0, 0, 0); G_SCHED; G_LDA(At, 0, 0); G_STAGE(G_SA(1, 1), a1 + hstep);
;             G_WAIT_L(8); G_BAR; G_WAIT_L(0); G_MMA(0, 0, At, B0); G_BAR; G_SCHED;
;             G_LDB(B1, 0, 1); G_STAGE(G_SB(0, 0), b2);
;             G_BAR; G_WAIT_L(0); G_MMA(0, 1, At, B1); G_BAR;
;             G_LDA(At, 0, 1); G_STAGE(G_SA(0, 0), a2);
;             G_BAR; G_WAIT_L(0); G_MMA(1, 0, At, B0); G_BAR; G_SCHED;
;             G_STAGE(G_SB(0, 1), b2 + hstep);
;             G_WAIT_V(6); G_BAR; G_MMA(1, 1, At, B1); G_BAR;
.LBB0_848:
	s_add_u32 s26, s50, 0xfffc0080
	s_addc_u32 s54, s51, -1
	s_and_b64 s[52:53], s[52:53], exec
	s_cselect_b32 s55, s54, s25
	s_cselect_b32 s54, s26, s24
	s_cselect_b32 s53, s71, s14
	s_cselect_b32 s52, s70, s15
	s_add_i32 m0, s60, 0xc000
.LmainW_848:
	ds_read_b128 v[130:133], v217
	ds_read_b128 v[134:137], v217 offset:1024
	ds_read_b128 v[144:147], v217 offset:2048
	ds_read_b128 v[148:151], v217 offset:3072
	ds_read_b128 v[156:159], v222
	ds_read_b128 v[160:163], v222 offset:1024
	ds_read_b128 v[164:167], v222 offset:2048
	ds_read_b128 v[180:183], v222 offset:3072
	ds_read_b128 v[184:187], v222 offset:4096
	ds_read_b128 v[224:227], v222 offset:5120
	ds_read_b128 v[228:231], v222 offset:6144
	global_load_lds_dwordx4 v170, s[50:51]
	s_add_i32 m0, s60, 0xe000
	ds_read_b128 v[232:235], v222 offset:7168
	global_load_lds_dwordx4 v168, s[50:51]
	s_waitcnt lgkmcnt(8)
	s_barrier
	s_waitcnt lgkmcnt(0)
	v_mfma_f32_16x16x32_bf16 v[152:155], v[130:133], v[156:159], v[152:155]
	v_mfma_f32_16x16x32_bf16 v[138:141], v[144:147], v[156:159], v[140:143]
	v_mfma_f32_16x16x32_bf16 v[116:119], v[130:133], v[164:167], v[116:119]
	v_mfma_f32_16x16x32_bf16 v[112:115], v[144:147], v[164:167], v[112:115]
	v_mfma_f32_16x16x32_bf16 v[100:103], v[130:133], v[184:187], v[100:103]
	v_mfma_f32_16x16x32_bf16 v[96:99], v[144:147], v[184:187], v[96:99]
	v_mfma_f32_16x16x32_bf16 v[84:87], v[130:133], v[228:231], v[84:87]
	v_mfma_f32_16x16x32_bf16 v[80:83], v[144:147], v[228:231], v[80:83]
	v_mfma_f32_16x16x32_bf16 v[152:155], v[134:137], v[160:163], v[152:155]
	v_mfma_f32_16x16x32_bf16 v[138:141], v[148:151], v[160:163], v[138:141]
	v_mfma_f32_16x16x32_bf16 v[116:119], v[134:137], v[180:183], v[116:119]
	v_mfma_f32_16x16x32_bf16 v[112:115], v[148:151], v[180:183], v[112:115]
	v_mfma_f32_16x16x32_bf16 v[100:103], v[134:137], v[224:227], v[100:103]
	v_mfma_f32_16x16x32_bf16 v[96:99], v[148:151], v[224:227], v[96:99]
	v_mfma_f32_16x16x32_bf16 v[84:87], v[134:137], v[232:235], v[84:87]
	v_mfma_f32_16x16x32_bf16 v[80:83], v[148:151], v[232:235], v[80:83]
	s_add_i32 m0, s59, 0x10000
	s_barrier
	ds_read_b128 v[236:239], v217 offset:16384
	ds_read_b128 v[240:243], v217 offset:17408
	ds_read_b128 v[244:247], v217 offset:18432
	global_load_lds_dwordx4 v0, s[52:53]
	s_add_i32 m0, s59, 0x12000
	ds_read_b128 v[248:251], v217 offset:19456
	global_load_lds_dwordx4 v2, s[52:53]
	s_barrier
	s_waitcnt lgkmcnt(0)
	v_mfma_f32_16x16x32_bf16 v[124:127], v[236:239], v[156:159], v[124:127]
	v_mfma_f32_16x16x32_bf16 v[120:123], v[244:247], v[156:159], v[120:123]
	v_mfma_f32_16x16x32_bf16 v[108:111], v[236:239], v[164:167], v[108:111]
	v_mfma_f32_16x16x32_bf16 v[104:107], v[244:247], v[164:167], v[104:107]
	v_mfma_f32_16x16x32_bf16 v[92:95], v[236:239], v[184:187], v[92:95]
	v_mfma_f32_16x16x32_bf16 v[88:91], v[244:247], v[184:187], v[88:91]
	v_mfma_f32_16x16x32_bf16 v[76:79], v[236:239], v[228:231], v[76:79]
	v_mfma_f32_16x16x32_bf16 v[72:75], v[244:247], v[228:231], v[72:75]
	v_mfma_f32_16x16x32_bf16 v[124:127], v[240:243], v[160:163], v[124:127]
	v_mfma_f32_16x16x32_bf16 v[120:123], v[248:251], v[160:163], v[120:123]
	v_mfma_f32_16x16x32_bf16 v[108:111], v[240:243], v[180:183], v[108:111]
	v_mfma_f32_16x16x32_bf16 v[104:107], v[248:251], v[180:183], v[104:107]
	v_mfma_f32_16x16x32_bf16 v[92:95], v[240:243], v[224:227], v[92:95]
	v_mfma_f32_16x16x32_bf16 v[88:91], v[248:251], v[224:227], v[88:91]
	v_mfma_f32_16x16x32_bf16 v[76:79], v[240:243], v[232:235], v[76:79]
	v_mfma_f32_16x16x32_bf16 v[72:75], v[248:251], v[232:235], v[72:75]
	s_mov_b32 m0, s60
	s_add_u32 s76, s54, 0x80
	s_addc_u32 s77, s55, 0
	s_barrier
	ds_read_b128 v[156:159], v222 offset:16384
	ds_read_b128 v[160:163], v222 offset:17408
	ds_read_b128 v[164:167], v222 offset:18432
	ds_read_b128 v[180:183], v222 offset:19456
	ds_read_b128 v[184:187], v222 offset:20480
	ds_read_b128 v[224:227], v222 offset:21504
	ds_read_b128 v[228:231], v222 offset:22528
	ds_read_b128 v[232:235], v222 offset:23552
	global_load_lds_dwordx4 v0, s[54:55]
	s_add_u32 s76, s54, 0x80
	s_mov_b32 m0, s61
	s_addc_u32 s77, s55, 0
	global_load_lds_dwordx4 v2, s[54:55]
	s_barrier
	s_waitcnt lgkmcnt(0)
	v_mfma_f32_16x16x32_bf16 v[60:63], v[130:133], v[156:159], v[60:63]
	v_mfma_f32_16x16x32_bf16 v[56:59], v[144:147], v[156:159], v[56:59]
	v_mfma_f32_16x16x32_bf16 v[44:47], v[130:133], v[164:167], v[44:47]
	v_mfma_f32_16x16x32_bf16 v[40:43], v[144:147], v[164:167], v[40:43]
	v_mfma_f32_16x16x32_bf16 v[28:31], v[130:133], v[184:187], v[28:31]
	v_mfma_f32_16x16x32_bf16 v[24:27], v[144:147], v[184:187], v[24:27]
	v_mfma_f32_16x16x32_bf16 v[12:15], v[130:133], v[228:231], v[12:15]
	v_mfma_f32_16x16x32_bf16 v[8:11], v[144:147], v[228:231], v[8:11]
	v_mfma_f32_16x16x32_bf16 v[60:63], v[134:137], v[160:163], v[60:63]
	v_mfma_f32_16x16x32_bf16 v[56:59], v[148:151], v[160:163], v[56:59]
	v_mfma_f32_16x16x32_bf16 v[44:47], v[134:137], v[180:183], v[44:47]
	v_mfma_f32_16x16x32_bf16 v[40:43], v[148:151], v[180:183], v[40:43]
	v_mfma_f32_16x16x32_bf16 v[28:31], v[134:137], v[224:227], v[28:31]
	v_mfma_f32_16x16x32_bf16 v[24:27], v[148:151], v[224:227], v[24:27]
	v_mfma_f32_16x16x32_bf16 v[12:15], v[134:137], v[232:235], v[12:15]
	v_mfma_f32_16x16x32_bf16 v[8:11], v[148:151], v[232:235], v[8:11]
	s_add_i32 m0, s59, 0x14000
	s_add_u32 s74, s52, 0x40000
	s_addc_u32 s75, s53, 0
	s_barrier
	global_load_lds_dwordx4 v0, s[74:75]
	s_add_i32 m0, s59, 0x16000
	s_add_u32 s54, s54, 0x40000
	s_addc_u32 s55, s55, 0
	global_load_lds_dwordx4 v2, s[74:75]
	s_waitcnt vmcnt(6)
	s_barrier
; #define G_STAGE(bufoff, gbase) do { _Pragma("unroll") for (int _i = 0; _i < 2; ++_i) \
;         __builtin_amdgcn_global_load_lds((const unsigned*)((const char*)(gbase) + voff[_i]), (LAS unsigned*)(lds + (bufoff) + ldsw + _i * 8192), 16, 0, 0); } while (0)
; #define G_LDA(dst, b, h) do { _Pragma("unroll") for (int m = 0; m < 4; ++m) _Pragma("unroll") for (int k = 0; k < 2; ++k) dst[m][k] = *(const LAS bf16x8*)(lds + G_SA(b, h) + aoff + m * 2048 + k * 1024); } while (0)
; #define G_LDB(dst, b, h) do { _Pragma("unroll") for (int n = 0; n < 2; ++n) _Pragma("unroll") for (int k = 0; k < 2; ++k) dst[n][k] = *(const LAS bf16x8*)(lds + G_SB(b, h) + boff + n * 2048 + k * 1024); } while (0)
; #define G_MMA(ai, bj, At, Bt) do { __builtin_amdgcn_s_setprio(1); _Pragma("unroll") for (int m = 0; m < 4; ++m) _Pragma("unroll") for (int n = 0; n < 2; ++n) _Pragma("unroll") for (int k = 0; k < 2; ++k) \
;         acc[ai][bj][m][n] = MFMA16(Bt[n][k], At[m][k], acc[ai][bj][m][n]); __builtin_amdgcn_s_setprio(0); } while (0)
; #define G_WAIT_V(n) asm volatile("s_waitcnt vmcnt(" #n ")" ::: "memory")
; #define G_WAIT_L(n) asm volatile("s_waitcnt lgkmcnt(" #n ")" ::: "memory")
; #define G_BAR __builtin_amdgcn_s_barrier()
; #define G_SCHED __builtin_amdgcn_sched_barrier(0)
; template <class Epi>
; __device__ __forceinline__ void gemm_phase(LAS unsigned char* lds, const bf16_t* Ag, const bf16_t* Btg, const int K, const int nM, const int nN, const Epi& E) {
;     ...
;         for (int t = 0; t < nt; t += 2) {
;             const bool last = (t == nt - 2);
;             const char* a1 = cA + (size_t)(t + 1) * kstep;
;             const char* a2 = last ? nA : cA + (size_t)(t + 2) * kstep; const char* b2 = last ? nB : cB + (size_t)(t + 2) * kstep;
;             const char* a3 = a2 + kstep; const char* b3 = b2 + kstep;
;     ...
;             G_LDB(B0, 1, 0); G_SCHED; G_LDA(At, 1, 0); G_STAGE(G_SA(0, 1), a2 + hstep);
;             G_WAIT_L(8); G_BAR; G_WAIT_L(0); G_MMA(0, 0, At, B0); G_BAR; G_SCHED;
;             G_LDB(B1, 1, 1); G_STAGE(G_SB(1, 0), b3);
;             G_BAR; G_WAIT_L(0); G_MMA(0, 1, At, B1); G_BAR;
;             G_LDA(At, 1, 1); G_STAGE(G_SA(1, 0), a3);
;             G_BAR; G_WAIT_L(0); G_MMA(1, 0, At, B0); G_BAR; G_SCHED;
;             G_STAGE(G_SB(1, 1), b3 + hstep);
;             G_WAIT_V(6); G_BAR; G_MMA(1, 1, At, B1); G_BAR;
	v_mfma_f32_16x16x32_bf16 v[68:71], v[236:239], v[156:159], v[68:71]
	v_mfma_f32_16x16x32_bf16 v[64:67], v[244:247], v[156:159], v[64:67]
	v_mfma_f32_16x16x32_bf16 v[52:55], v[236:239], v[164:167], v[52:55]
	v_mfma_f32_16x16x32_bf16 v[48:51], v[244:247], v[164:167], v[48:51]
	v_mfma_f32_16x16x32_bf16 v[36:39], v[236:239], v[184:187], v[36:39]
	v_mfma_f32_16x16x32_bf16 v[32:35], v[244:247], v[184:187], v[32:35]
	v_mfma_f32_16x16x32_bf16 v[20:23], v[236:239], v[228:231], v[20:23]
	v_mfma_f32_16x16x32_bf16 v[16:19], v[244:247], v[228:231], v[16:19]
	v_mfma_f32_16x16x32_bf16 v[68:71], v[240:243], v[160:163], v[68:71]
	v_mfma_f32_16x16x32_bf16 v[64:67], v[248:251], v[160:163], v[64:67]
	v_mfma_f32_16x16x32_bf16 v[52:55], v[240:243], v[180:183], v[52:55]
	v_mfma_f32_16x16x32_bf16 v[48:51], v[248:251], v[180:183], v[48:51]
	v_mfma_f32_16x16x32_bf16 v[36:39], v[240:243], v[224:227], v[36:39]
	v_mfma_f32_16x16x32_bf16 v[32:35], v[248:251], v[224:227], v[32:35]
	v_mfma_f32_16x16x32_bf16 v[20:23], v[240:243], v[232:235], v[20:23]
	v_mfma_f32_16x16x32_bf16 v[16:19], v[248:251], v[232:235], v[16:19]
	s_mov_b32 m0, s62
	s_barrier
	ds_read_b128 v[130:133], v217 offset:32768
	ds_read_b128 v[134:137], v217 offset:33792
	ds_read_b128 v[144:147], v217 offset:34816
	ds_read_b128 v[148:151], v217 offset:35840
	ds_read_b128 v[156:159], v222 offset:32768
	ds_read_b128 v[160:163], v222 offset:33792
	ds_read_b128 v[164:167], v222 offset:34816
	ds_read_b128 v[180:183], v222 offset:35840
	ds_read_b128 v[184:187], v222 offset:36864
	ds_read_b128 v[224:227], v222 offset:37888
	ds_read_b128 v[228:231], v222 offset:38912
	global_load_lds_dwordx4 v0, s[54:55]
	s_mov_b32 m0, s63
	ds_read_b128 v[232:235], v222 offset:39936
	global_load_lds_dwordx4 v2, s[54:55]
	s_waitcnt lgkmcnt(8)
	s_barrier
	s_waitcnt lgkmcnt(0)
	v_mfma_f32_16x16x32_bf16 v[152:155], v[130:133], v[156:159], v[152:155]
	v_mfma_f32_16x16x32_bf16 v[138:141], v[144:147], v[156:159], v[138:141]
	v_mfma_f32_16x16x32_bf16 v[116:119], v[130:133], v[164:167], v[116:119]
	v_mfma_f32_16x16x32_bf16 v[112:115], v[144:147], v[164:167], v[112:115]
	v_mfma_f32_16x16x32_bf16 v[100:103], v[130:133], v[184:187], v[100:103]
	v_mfma_f32_16x16x32_bf16 v[96:99], v[144:147], v[184:187], v[96:99]
	v_mfma_f32_16x16x32_bf16 v[84:87], v[130:133], v[228:231], v[84:87]
	v_mfma_f32_16x16x32_bf16 v[80:83], v[144:147], v[228:231], v[80:83]
	v_mfma_f32_16x16x32_bf16 v[152:155], v[134:137], v[160:163], v[152:155]
	v_mfma_f32_16x16x32_bf16 v[140:143], v[148:151], v[160:163], v[138:141]
	v_mfma_f32_16x16x32_bf16 v[116:119], v[134:137], v[180:183], v[116:119]
	v_mfma_f32_16x16x32_bf16 v[112:115], v[148:151], v[180:183], v[112:115]
	v_mfma_f32_16x16x32_bf16 v[100:103], v[134:137], v[224:227], v[100:103]
	v_mfma_f32_16x16x32_bf16 v[96:99], v[148:151], v[224:227], v[96:99]
	v_mfma_f32_16x16x32_bf16 v[84:87], v[134:137], v[232:235], v[84:87]
	v_mfma_f32_16x16x32_bf16 v[80:83], v[148:151], v[232:235], v[80:83]
	s_add_i32 m0, s59, 0x18000
	s_add_u32 s98, s52, 0x80
	s_addc_u32 s99, s53, 0
	s_barrier
	ds_read_b128 v[236:239], v217 offset:49152
	ds_read_b128 v[240:243], v217 offset:50176
	ds_read_b128 v[244:247], v217 offset:51200
	global_load_lds_dwordx4 v0, s[98:99]
	s_add_i32 m0, s59, 0x1a000
	ds_read_b128 v[248:251], v217 offset:52224
	global_load_lds_dwordx4 v2, s[98:99]
	s_barrier
	s_waitcnt lgkmcnt(0)
	v_mfma_f32_16x16x32_bf16 v[124:127], v[236:239], v[156:159], v[124:127]
	v_mfma_f32_16x16x32_bf16 v[120:123], v[244:247], v[156:159], v[120:123]
	v_mfma_f32_16x16x32_bf16 v[108:111], v[236:239], v[164:167], v[108:111]
	v_mfma_f32_16x16x32_bf16 v[104:107], v[244:247], v[164:167], v[104:107]
	v_mfma_f32_16x16x32_bf16 v[92:95], v[236:239], v[184:187], v[92:95]
	v_mfma_f32_16x16x32_bf16 v[88:91], v[244:247], v[184:187], v[88:91]
	v_mfma_f32_16x16x32_bf16 v[76:79], v[236:239], v[228:231], v[76:79]
	v_mfma_f32_16x16x32_bf16 v[72:75], v[244:247], v[228:231], v[72:75]
	v_mfma_f32_16x16x32_bf16 v[124:127], v[240:243], v[160:163], v[124:127]
	v_mfma_f32_16x16x32_bf16 v[120:123], v[248:251], v[160:163], v[120:123]
	v_mfma_f32_16x16x32_bf16 v[108:111], v[240:243], v[180:183], v[108:111]
	v_mfma_f32_16x16x32_bf16 v[104:107], v[248:251], v[180:183], v[104:107]
	v_mfma_f32_16x16x32_bf16 v[92:95], v[240:243], v[224:227], v[92:95]
	v_mfma_f32_16x16x32_bf16 v[88:91], v[248:251], v[224:227], v[88:91]
	v_mfma_f32_16x16x32_bf16 v[76:79], v[240:243], v[232:235], v[76:79]
	v_mfma_f32_16x16x32_bf16 v[72:75], v[248:251], v[232:235], v[72:75]
	s_mov_b32 m0, s64
	s_barrier
	ds_read_b128 v[156:159], v222 offset:49152
	ds_read_b128 v[160:163], v222 offset:50176
	ds_read_b128 v[164:167], v222 offset:51200
	ds_read_b128 v[180:183], v222 offset:52224
	ds_read_b128 v[184:187], v222 offset:53248
	ds_read_b128 v[224:227], v222 offset:54272
	ds_read_b128 v[228:231], v222 offset:55296
	global_load_lds_dwordx4 v0, s[76:77]
	s_mov_b32 m0, s65
	ds_read_b128 v[232:235], v222 offset:56320
	global_load_lds_dwordx4 v2, s[76:77]
	s_barrier
	s_waitcnt lgkmcnt(0)
	v_mfma_f32_16x16x32_bf16 v[60:63], v[130:133], v[156:159], v[60:63]
	v_mfma_f32_16x16x32_bf16 v[56:59], v[144:147], v[156:159], v[56:59]
	v_mfma_f32_16x16x32_bf16 v[44:47], v[130:133], v[164:167], v[44:47]
	v_mfma_f32_16x16x32_bf16 v[40:43], v[144:147], v[164:167], v[40:43]
	v_mfma_f32_16x16x32_bf16 v[28:31], v[130:133], v[184:187], v[28:31]
	v_mfma_f32_16x16x32_bf16 v[24:27], v[144:147], v[184:187], v[24:27]
	v_mfma_f32_16x16x32_bf16 v[12:15], v[130:133], v[228:231], v[12:15]
	v_mfma_f32_16x16x32_bf16 v[8:11], v[144:147], v[228:231], v[8:11]
	v_mfma_f32_16x16x32_bf16 v[60:63], v[134:137], v[160:163], v[60:63]
	v_mfma_f32_16x16x32_bf16 v[56:59], v[148:151], v[160:163], v[56:59]
	v_mfma_f32_16x16x32_bf16 v[44:47], v[134:137], v[180:183], v[44:47]
	v_mfma_f32_16x16x32_bf16 v[40:43], v[148:151], v[180:183], v[40:43]
	v_mfma_f32_16x16x32_bf16 v[28:31], v[134:137], v[224:227], v[28:31]
	v_mfma_f32_16x16x32_bf16 v[24:27], v[148:151], v[224:227], v[24:27]
	v_mfma_f32_16x16x32_bf16 v[12:15], v[134:137], v[232:235], v[12:15]
	v_mfma_f32_16x16x32_bf16 v[8:11], v[148:151], v[232:235], v[8:11]
	s_add_i32 m0, s59, 0x1c000
	s_add_u32 s52, s52, 0x40080
	s_addc_u32 s53, s53, 0
	s_barrier
	global_load_lds_dwordx4 v0, s[52:53]
	s_add_i32 m0, s59, 0x1e000
	s_add_i32 s72, s72, 2
	global_load_lds_dwordx4 v2, s[52:53]
	s_add_u32 s70, s70, 0x100
	s_addc_u32 s71, s71, 0
	s_add_u32 s50, s50, 0x100
	s_addc_u32 s51, s51, 0
	s_cmp_gt_u32 s72, 13
	s_cbranch_scc1 .LrotX_848
	s_add_u32 s26, s50, 0xfffc0080
	s_addc_u32 s54, s51, -1
	s_cmp_lg_u32 s72, 12
	s_cselect_b32 s55, s54, s25
	s_cselect_b32 s54, s26, s24
	s_cselect_b32 s53, s71, s14
	s_cselect_b32 s52, s70, s15
; #define G_STAGE(bufoff, gbase) do { _Pragma("unroll") for (int _i = 0; _i < 2; ++_i) \
;         __builtin_amdgcn_global_load_lds((const unsigned*)((const char*)(gbase) + voff[_i]), (LAS unsigned*)(lds + (bufoff) + ldsw + _i * 8192), 16, 0, 0); } while (0)
; #define G_MMA(ai, bj, At, Bt) do { __builtin_amdgcn_s_setprio(1); _Pragma("unroll") for (int m = 0; m < 4; ++m) _Pragma("unroll") for (int n = 0; n < 2; ++n) _Pragma("unroll") for (int k = 0; k < 2; ++k) \
;         acc[ai][bj][m][n] = MFMA16(Bt[n][k], At[m][k], acc[ai][bj][m][n]); __builtin_amdgcn_s_setprio(0); } while (0)
; #define G_WAIT_V(n) asm volatile("s_waitcnt vmcnt(" #n ")" ::: "memory")
; #define G_BAR __builtin_amdgcn_s_barrier()
; template <class Epi>
; __device__ __forceinline__ void gemm_phase(LAS unsigned char* lds, const bf16_t* Ag, const bf16_t* Btg, const int K, const int nM, const int nN, const Epi& E) {
;     ...
;             G_STAGE(G_SB(1, 1), b3 + hstep);
;             G_WAIT_V(6); G_BAR; G_MMA(1, 1, At, B1); G_BAR;
;         }
.LrotX_848:
	s_waitcnt vmcnt(6)
	s_barrier
	v_mfma_f32_16x16x32_bf16 v[68:71], v[236:239], v[156:159], v[68:71]
	v_mfma_f32_16x16x32_bf16 v[64:67], v[244:247], v[156:159], v[64:67]
	v_mfma_f32_16x16x32_bf16 v[52:55], v[236:239], v[164:167], v[52:55]
	v_mfma_f32_16x16x32_bf16 v[48:51], v[244:247], v[164:167], v[48:51]
	v_mfma_f32_16x16x32_bf16 v[36:39], v[236:239], v[184:187], v[36:39]
	v_mfma_f32_16x16x32_bf16 v[32:35], v[244:247], v[184:187], v[32:35]
	v_mfma_f32_16x16x32_bf16 v[20:23], v[236:239], v[228:231], v[20:23]
	v_mfma_f32_16x16x32_bf16 v[16:19], v[244:247], v[228:231], v[16:19]
	v_mfma_f32_16x16x32_bf16 v[68:71], v[240:243], v[160:163], v[68:71]
	v_mfma_f32_16x16x32_bf16 v[64:67], v[248:251], v[160:163], v[64:67]
	v_mfma_f32_16x16x32_bf16 v[52:55], v[240:243], v[180:183], v[52:55]
	v_mfma_f32_16x16x32_bf16 v[48:51], v[248:251], v[180:183], v[48:51]
	v_mfma_f32_16x16x32_bf16 v[36:39], v[240:243], v[224:227], v[36:39]
	v_mfma_f32_16x16x32_bf16 v[32:35], v[248:251], v[224:227], v[32:35]
	v_mfma_f32_16x16x32_bf16 v[20:23], v[240:243], v[232:235], v[20:23]
	v_mfma_f32_16x16x32_bf16 v[16:19], v[248:251], v[232:235], v[16:19]
	s_add_i32 m0, s60, 0xc000
	s_cmp_lt_u32 s72, 12
	s_barrier
	s_cbranch_scc1 .LmainW_848
	s_cmp_gt_u32 s72, 13
	s_cbranch_scc1 .LBB0_852
